# P4+P10 epilogue load hoisting, P9 role-split K/V prefetch, P2 vmcnt hoist
# speedup vs baseline: 1.0205x; 1.0205x over previous
.LBB0_308:
	v_mov_b32_e32 v2, v0
	v_mov_b32_e32 v3, v0
	v_mov_b32_e32 v1, v0
	v_mov_b64_e32 v[144:145], v[2:3]
	v_mov_b64_e32 v[140:141], v[2:3]
	v_mov_b64_e32 v[128:129], v[2:3]
	v_mov_b64_e32 v[124:125], v[2:3]
	v_mov_b64_e32 v[112:113], v[2:3]
	v_mov_b64_e32 v[108:109], v[2:3]
	v_mov_b64_e32 v[96:97], v[2:3]
	v_mov_b64_e32 v[92:93], v[2:3]
	v_mov_b64_e32 v[136:137], v[2:3]
	v_mov_b64_e32 v[132:133], v[2:3]
	v_mov_b64_e32 v[120:121], v[2:3]
	v_mov_b64_e32 v[116:117], v[2:3]
	v_mov_b64_e32 v[104:105], v[2:3]
	v_mov_b64_e32 v[100:101], v[2:3]
	v_mov_b64_e32 v[88:89], v[2:3]
	v_mov_b64_e32 v[84:85], v[2:3]
	v_mov_b64_e32 v[80:81], v[2:3]
	v_mov_b64_e32 v[76:77], v[2:3]
	v_mov_b64_e32 v[64:65], v[2:3]
	v_mov_b64_e32 v[60:61], v[2:3]
	v_mov_b64_e32 v[32:33], v[2:3]
	v_mov_b64_e32 v[28:29], v[2:3]
	v_mov_b64_e32 v[16:17], v[2:3]
	v_mov_b64_e32 v[12:13], v[2:3]
	v_mov_b64_e32 v[72:73], v[2:3]
	v_mov_b64_e32 v[68:69], v[2:3]
	v_mov_b64_e32 v[56:57], v[2:3]
	v_mov_b64_e32 v[52:53], v[2:3]
	v_mov_b64_e32 v[24:25], v[2:3]
	v_mov_b64_e32 v[20:21], v[2:3]
	v_mov_b64_e32 v[8:9], v[2:3]
	v_mov_b64_e32 v[142:143], v[0:1]
	v_mov_b64_e32 v[138:139], v[0:1]
	v_mov_b64_e32 v[126:127], v[0:1]
	v_mov_b64_e32 v[122:123], v[0:1]
	v_mov_b64_e32 v[110:111], v[0:1]
	v_mov_b64_e32 v[106:107], v[0:1]
	v_mov_b64_e32 v[94:95], v[0:1]
	v_mov_b64_e32 v[90:91], v[0:1]
	v_mov_b64_e32 v[134:135], v[0:1]
	v_mov_b64_e32 v[130:131], v[0:1]
	v_mov_b64_e32 v[118:119], v[0:1]
	v_mov_b64_e32 v[114:115], v[0:1]
	v_mov_b64_e32 v[102:103], v[0:1]
	v_mov_b64_e32 v[98:99], v[0:1]
	v_mov_b64_e32 v[86:87], v[0:1]
	v_mov_b64_e32 v[82:83], v[0:1]
	v_mov_b64_e32 v[78:79], v[0:1]
	v_mov_b64_e32 v[74:75], v[0:1]
	v_mov_b64_e32 v[62:63], v[0:1]
	v_mov_b64_e32 v[58:59], v[0:1]
	v_mov_b64_e32 v[30:31], v[0:1]
	v_mov_b64_e32 v[26:27], v[0:1]
	v_mov_b64_e32 v[14:15], v[0:1]
	v_mov_b64_e32 v[10:11], v[0:1]
	v_mov_b64_e32 v[70:71], v[0:1]
	v_mov_b64_e32 v[66:67], v[0:1]
	v_mov_b64_e32 v[54:55], v[0:1]
	v_mov_b64_e32 v[50:51], v[0:1]
	v_mov_b64_e32 v[22:23], v[0:1]
	v_mov_b64_e32 v[18:19], v[0:1]
	v_mov_b64_e32 v[6:7], v[0:1]
	v_mov_b64_e32 v[4:5], v[2:3]
	s_andn2_b64 vcc, exec, s[36:37]
	v_mov_b64_e32 v[2:3], v[0:1]
	s_cbranch_vccnz .LBB0_311
	s_add_u32 s4, s10, 0x80
	s_addc_u32 s5, s11, 0
	s_add_u32 s8, s8, 0x100
	v_mov_b32_e32 v2, 0
	s_addc_u32 s9, s9, 0
	s_mov_b32 s6, 0
	v_mov_b32_e32 v3, v2
	v_mov_b32_e32 v4, v2
	v_mov_b32_e32 v5, v2
	v_mov_b32_e32 v6, v2
	v_mov_b32_e32 v7, v2
	v_mov_b32_e32 v8, v2
	v_mov_b32_e32 v9, v2
	v_mov_b32_e32 v18, v2
	v_mov_b32_e32 v19, v2
	v_mov_b32_e32 v20, v2
	v_mov_b32_e32 v21, v2
	v_mov_b32_e32 v22, v2
	v_mov_b32_e32 v23, v2
	v_mov_b32_e32 v24, v2
	v_mov_b32_e32 v25, v2
	v_mov_b32_e32 v50, v2
	v_mov_b32_e32 v51, v2
	v_mov_b32_e32 v52, v2
	v_mov_b32_e32 v53, v2
	v_mov_b32_e32 v54, v2
	v_mov_b32_e32 v55, v2
	v_mov_b32_e32 v56, v2
	v_mov_b32_e32 v57, v2
	v_mov_b32_e32 v66, v2
	v_mov_b32_e32 v67, v2
	v_mov_b32_e32 v68, v2
	v_mov_b32_e32 v69, v2
	v_mov_b32_e32 v70, v2
	v_mov_b32_e32 v71, v2
	v_mov_b32_e32 v72, v2
	v_mov_b32_e32 v73, v2
	v_mov_b32_e32 v10, v2
	v_mov_b32_e32 v11, v2
	v_mov_b32_e32 v12, v2
	v_mov_b32_e32 v13, v2
	v_mov_b32_e32 v14, v2
	v_mov_b32_e32 v15, v2
	v_mov_b32_e32 v16, v2
	v_mov_b32_e32 v17, v2
	v_mov_b32_e32 v26, v2
	v_mov_b32_e32 v27, v2
	v_mov_b32_e32 v28, v2
	v_mov_b32_e32 v29, v2
	v_mov_b32_e32 v30, v2
	v_mov_b32_e32 v31, v2
	v_mov_b32_e32 v32, v2
	v_mov_b32_e32 v33, v2
	v_mov_b32_e32 v58, v2
	v_mov_b32_e32 v59, v2
	v_mov_b32_e32 v60, v2
	v_mov_b32_e32 v61, v2
	v_mov_b32_e32 v62, v2
	v_mov_b32_e32 v63, v2
	v_mov_b32_e32 v64, v2
	v_mov_b32_e32 v65, v2
	v_mov_b32_e32 v74, v2
	v_mov_b32_e32 v75, v2
	v_mov_b32_e32 v76, v2
	v_mov_b32_e32 v77, v2
	v_mov_b32_e32 v78, v2
	v_mov_b32_e32 v79, v2
	v_mov_b32_e32 v80, v2
	v_mov_b32_e32 v81, v2
	v_mov_b32_e32 v82, v2
	v_mov_b32_e32 v83, v2
	v_mov_b32_e32 v84, v2
	v_mov_b32_e32 v85, v2
	v_mov_b32_e32 v86, v2
	v_mov_b32_e32 v87, v2
	v_mov_b32_e32 v88, v2
	v_mov_b32_e32 v89, v2
	v_mov_b32_e32 v98, v2
	v_mov_b32_e32 v99, v2
	v_mov_b32_e32 v100, v2
	v_mov_b32_e32 v101, v2
	v_mov_b32_e32 v102, v2
	v_mov_b32_e32 v103, v2
	v_mov_b32_e32 v104, v2
	v_mov_b32_e32 v105, v2
	v_mov_b32_e32 v114, v2
	v_mov_b32_e32 v115, v2
	v_mov_b32_e32 v116, v2
	v_mov_b32_e32 v117, v2
	v_mov_b32_e32 v118, v2
	v_mov_b32_e32 v119, v2
	v_mov_b32_e32 v120, v2
	v_mov_b32_e32 v121, v2
	v_mov_b32_e32 v130, v2
	v_mov_b32_e32 v131, v2
	v_mov_b32_e32 v132, v2
	v_mov_b32_e32 v133, v2
	v_mov_b32_e32 v134, v2
	v_mov_b32_e32 v135, v2
	v_mov_b32_e32 v136, v2
	v_mov_b32_e32 v137, v2
	v_mov_b32_e32 v90, v2
	v_mov_b32_e32 v91, v2
	v_mov_b32_e32 v92, v2
	v_mov_b32_e32 v93, v2
	v_mov_b32_e32 v94, v2
	v_mov_b32_e32 v95, v2
	v_mov_b32_e32 v96, v2
	v_mov_b32_e32 v97, v2
	v_mov_b32_e32 v106, v2
	v_mov_b32_e32 v107, v2
	v_mov_b32_e32 v108, v2
	v_mov_b32_e32 v109, v2
	v_mov_b32_e32 v110, v2
	v_mov_b32_e32 v111, v2
	v_mov_b32_e32 v112, v2
	v_mov_b32_e32 v113, v2
	v_mov_b32_e32 v122, v2
	v_mov_b32_e32 v123, v2
	v_mov_b32_e32 v124, v2
	v_mov_b32_e32 v125, v2
	v_mov_b32_e32 v126, v2
	v_mov_b32_e32 v127, v2
	v_mov_b32_e32 v128, v2
	v_mov_b32_e32 v129, v2
	v_mov_b32_e32 v138, v2
	v_mov_b32_e32 v139, v2
	v_mov_b32_e32 v140, v2
	v_mov_b32_e32 v141, v2
	v_mov_b32_e32 v142, v2
	v_mov_b32_e32 v143, v2
	v_mov_b32_e32 v144, v2
	v_mov_b32_e32 v145, v2
	s_waitcnt vmcnt(0)
.LBB0_310:
	ds_read_b128 v[34:37], v202
	ds_read_b128 v[38:41], v202 offset:1024
	ds_read_b128 v[42:45], v202 offset:2048
	ds_read_b128 v[46:49], v202 offset:3072
	ds_read_b128 v[146:149], v203
	ds_read_b128 v[150:153], v203 offset:1024
	ds_read_b128 v[154:157], v203 offset:2048
	ds_read_b128 v[158:161], v203 offset:3072
	s_add_i32 s10, s6, 2
	s_add_u32 s11, s4, 0x80
	s_addc_u32 s7, s5, 0
	s_cmp_eq_u32 s87, s6
	s_cselect_b32 s6, s42, s11
	s_cselect_b32 s7, s43, s7
	s_cselect_b32 s47, s45, s9
	s_cselect_b32 s46, s44, s8
	v_lshl_add_u64 v[196:197], s[4:5], 0, v[184:185]
	s_add_i32 m0, s57, 0xc000
	ds_read_b128 v[192:195], v204
	ds_read_b128 v[208:211], v204 offset:1024
	ds_read_b128 v[212:215], v204 offset:2048
	ds_read_b128 v[216:219], v204 offset:3072
	ds_read_b128 v[220:223], v204 offset:4096
	ds_read_b128 v[224:227], v204 offset:5120
	ds_read_b128 v[228:231], v204 offset:6144
	ds_read_b128 v[232:235], v204 offset:7168
	global_load_lds_dwordx4 v[196:197], off
	v_lshl_add_u64 v[196:197], s[4:5], 0, v[186:187]
	s_add_i32 m0, s57, 0xe000
	s_nop 0
	global_load_lds_dwordx4 v[196:197], off
	s_waitcnt vmcnt(8)
	s_waitcnt lgkmcnt(0)
	s_barrier
	s_setprio 1
	s_waitcnt lgkmcnt(0)
	v_mfma_f32_16x16x32_bf16 v[142:145], v[34:37], v[192:195], v[142:145]
	v_mfma_f32_16x16x32_bf16 v[138:141], v[42:45], v[192:195], v[138:141]
	v_mfma_f32_16x16x32_bf16 v[126:129], v[34:37], v[212:215], v[126:129]
	v_mfma_f32_16x16x32_bf16 v[122:125], v[42:45], v[212:215], v[122:125]
	v_mfma_f32_16x16x32_bf16 v[110:113], v[34:37], v[220:223], v[110:113]
	v_mfma_f32_16x16x32_bf16 v[106:109], v[42:45], v[220:223], v[106:109]
	v_mfma_f32_16x16x32_bf16 v[94:97], v[34:37], v[228:231], v[94:97]
	v_mfma_f32_16x16x32_bf16 v[90:93], v[42:45], v[228:231], v[90:93]
	v_mfma_f32_16x16x32_bf16 v[142:145], v[38:41], v[208:211], v[142:145]
	v_mfma_f32_16x16x32_bf16 v[138:141], v[46:49], v[208:211], v[138:141]
	v_mfma_f32_16x16x32_bf16 v[126:129], v[38:41], v[216:219], v[126:129]
	v_mfma_f32_16x16x32_bf16 v[122:125], v[46:49], v[216:219], v[122:125]
	v_mfma_f32_16x16x32_bf16 v[110:113], v[38:41], v[224:227], v[110:113]
	v_mfma_f32_16x16x32_bf16 v[106:109], v[46:49], v[224:227], v[106:109]
	v_mfma_f32_16x16x32_bf16 v[94:97], v[38:41], v[232:235], v[94:97]
	v_mfma_f32_16x16x32_bf16 v[90:93], v[46:49], v[232:235], v[90:93]
	s_setprio 0
	s_setprio 1
	v_mfma_f32_16x16x32_bf16 v[134:137], v[146:149], v[192:195], v[134:137]
	v_mfma_f32_16x16x32_bf16 v[130:133], v[154:157], v[192:195], v[130:133]
	v_mfma_f32_16x16x32_bf16 v[118:121], v[146:149], v[212:215], v[118:121]
	v_mfma_f32_16x16x32_bf16 v[114:117], v[154:157], v[212:215], v[114:117]
	v_mfma_f32_16x16x32_bf16 v[102:105], v[146:149], v[220:223], v[102:105]
	v_mfma_f32_16x16x32_bf16 v[98:101], v[154:157], v[220:223], v[98:101]
	v_mfma_f32_16x16x32_bf16 v[86:89], v[146:149], v[228:231], v[86:89]
	v_mfma_f32_16x16x32_bf16 v[82:85], v[154:157], v[228:231], v[82:85]
	v_mfma_f32_16x16x32_bf16 v[134:137], v[150:153], v[208:211], v[134:137]
	v_mfma_f32_16x16x32_bf16 v[130:133], v[158:161], v[208:211], v[130:133]
	v_mfma_f32_16x16x32_bf16 v[118:121], v[150:153], v[216:219], v[118:121]
	v_mfma_f32_16x16x32_bf16 v[114:117], v[158:161], v[216:219], v[114:117]
	v_mfma_f32_16x16x32_bf16 v[102:105], v[150:153], v[224:227], v[102:105]
	v_mfma_f32_16x16x32_bf16 v[98:101], v[158:161], v[224:227], v[98:101]
	v_mfma_f32_16x16x32_bf16 v[86:89], v[150:153], v[232:235], v[86:89]
	v_mfma_f32_16x16x32_bf16 v[82:85], v[158:161], v[232:235], v[82:85]
	s_setprio 0
	s_barrier
	s_add_i32 s11, s89, s56
	v_lshl_add_u64 v[196:197], s[46:47], 0, v[164:165]
	s_mov_b32 m0, s11
	ds_read_b128 v[192:195], v204 offset:16384
	ds_read_b128 v[208:211], v204 offset:17408
	ds_read_b128 v[212:215], v204 offset:18432
	ds_read_b128 v[216:219], v204 offset:19456
	ds_read_b128 v[220:223], v204 offset:20480
	ds_read_b128 v[224:227], v204 offset:21504
	ds_read_b128 v[228:231], v204 offset:22528
	ds_read_b128 v[232:235], v204 offset:23552
	global_load_lds_dwordx4 v[196:197], off
	s_add_i32 m0, s11, 0x2000
	v_lshl_add_u64 v[236:237], s[46:47], 0, v[168:169]
	s_add_u32 s46, s46, s26
	s_addc_u32 s47, s47, s27
	s_add_i32 s11, s90, s56
	global_load_lds_dwordx4 v[236:237], off
	v_lshl_add_u64 v[238:239], s[46:47], 0, v[164:165]
	s_mov_b32 m0, s11
	v_lshl_add_u64 v[240:241], s[46:47], 0, v[168:169]
	global_load_lds_dwordx4 v[238:239], off
	s_add_i32 m0, s11, 0x2000
	v_lshl_add_u64 v[242:243], s[6:7], 0, v[162:163]
	global_load_lds_dwordx4 v[240:241], off
	s_mov_b32 m0, s57
	v_lshl_add_u64 v[244:245], s[6:7], 0, v[166:167]
	global_load_lds_dwordx4 v[242:243], off
	s_mov_b32 m0, s58
	s_nop 0
	global_load_lds_dwordx4 v[244:245], off
	s_waitcnt vmcnt(8)
	s_waitcnt lgkmcnt(0)
	s_barrier
	s_setprio 1
	s_waitcnt lgkmcnt(0)
	v_mfma_f32_16x16x32_bf16 v[78:81], v[34:37], v[192:195], v[78:81]
	v_mfma_f32_16x16x32_bf16 v[74:77], v[42:45], v[192:195], v[74:77]
	v_mfma_f32_16x16x32_bf16 v[62:65], v[34:37], v[212:215], v[62:65]
	v_mfma_f32_16x16x32_bf16 v[58:61], v[42:45], v[212:215], v[58:61]
	v_mfma_f32_16x16x32_bf16 v[30:33], v[34:37], v[220:223], v[30:33]
	v_mfma_f32_16x16x32_bf16 v[26:29], v[42:45], v[220:223], v[26:29]
	v_mfma_f32_16x16x32_bf16 v[14:17], v[34:37], v[228:231], v[14:17]
	v_mfma_f32_16x16x32_bf16 v[10:13], v[42:45], v[228:231], v[10:13]
	v_mfma_f32_16x16x32_bf16 v[78:81], v[38:41], v[208:211], v[78:81]
	v_mfma_f32_16x16x32_bf16 v[74:77], v[46:49], v[208:211], v[74:77]
	v_mfma_f32_16x16x32_bf16 v[62:65], v[38:41], v[216:219], v[62:65]
	v_mfma_f32_16x16x32_bf16 v[58:61], v[46:49], v[216:219], v[58:61]
	v_mfma_f32_16x16x32_bf16 v[30:33], v[38:41], v[224:227], v[30:33]
	v_mfma_f32_16x16x32_bf16 v[26:29], v[46:49], v[224:227], v[26:29]
	v_mfma_f32_16x16x32_bf16 v[14:17], v[38:41], v[232:235], v[14:17]
	v_mfma_f32_16x16x32_bf16 v[10:13], v[46:49], v[232:235], v[10:13]
	s_setprio 0
	s_setprio 1
	v_mfma_f32_16x16x32_bf16 v[22:25], v[146:149], v[220:223], v[22:25]
	v_mfma_f32_16x16x32_bf16 v[18:21], v[154:157], v[220:223], v[18:21]
	v_mfma_f32_16x16x32_bf16 v[6:9], v[146:149], v[228:231], v[6:9]
	v_mfma_f32_16x16x32_bf16 v[2:5], v[154:157], v[228:231], v[2:5]
	v_mfma_f32_16x16x32_bf16 v[34:37], v[146:149], v[192:195], v[70:73]
	v_mfma_f32_16x16x32_bf16 v[38:41], v[154:157], v[192:195], v[66:69]
	v_mfma_f32_16x16x32_bf16 v[42:45], v[146:149], v[212:215], v[54:57]
	v_mfma_f32_16x16x32_bf16 v[46:49], v[154:157], v[212:215], v[50:53]
	v_mfma_f32_16x16x32_bf16 v[22:25], v[150:153], v[224:227], v[22:25]
	v_mfma_f32_16x16x32_bf16 v[18:21], v[158:161], v[224:227], v[18:21]
	v_mfma_f32_16x16x32_bf16 v[6:9], v[150:153], v[232:235], v[6:9]
	v_mfma_f32_16x16x32_bf16 v[2:5], v[158:161], v[232:235], v[2:5]
	v_mfma_f32_16x16x32_bf16 v[34:37], v[150:153], v[208:211], v[34:37]
	v_mfma_f32_16x16x32_bf16 v[38:41], v[158:161], v[208:211], v[38:41]
	v_mfma_f32_16x16x32_bf16 v[42:45], v[150:153], v[216:219], v[42:45]
	v_mfma_f32_16x16x32_bf16 v[46:49], v[158:161], v[216:219], v[46:49]
	s_setprio 0
	s_barrier
	s_add_i32 s11, 0, 0x18000
	v_add_u32_e32 v1, s11, v179
	s_add_i32 s46, 0, 0x1c000
	ds_read_b128 v[50:53], v1
	ds_read_b128 v[54:57], v1 offset:1024
	ds_read_b128 v[66:69], v1 offset:2048
	ds_read_b128 v[70:73], v1 offset:3072
	v_add_u32_e32 v1, s46, v179
	ds_read_b128 v[146:149], v1
	ds_read_b128 v[150:153], v1 offset:1024
	ds_read_b128 v[154:157], v1 offset:2048
	ds_read_b128 v[158:161], v1 offset:3072
	s_add_u32 s6, s6, s26
	s_addc_u32 s7, s7, s27
	s_mov_b32 m0, s59
	v_lshl_add_u64 v[246:247], s[6:7], 0, v[162:163]
	ds_read_b128 v[192:195], v204 offset:32768
	ds_read_b128 v[208:211], v204 offset:33792
	ds_read_b128 v[212:215], v204 offset:34816
	ds_read_b128 v[216:219], v204 offset:35840
	ds_read_b128 v[220:223], v204 offset:36864
	ds_read_b128 v[224:227], v204 offset:37888
	ds_read_b128 v[228:231], v204 offset:38912
	ds_read_b128 v[232:235], v204 offset:39936
	global_load_lds_dwordx4 v[246:247], off
	v_lshl_add_u64 v[246:247], s[6:7], 0, v[166:167]
	s_mov_b32 m0, s60
	s_nop 0
	global_load_lds_dwordx4 v[246:247], off
	s_waitcnt vmcnt(8)
	s_waitcnt lgkmcnt(0)
	s_barrier
	s_setprio 1
	s_waitcnt lgkmcnt(0)
	v_mfma_f32_16x16x32_bf16 v[142:145], v[50:53], v[192:195], v[142:145]
	v_mfma_f32_16x16x32_bf16 v[138:141], v[66:69], v[192:195], v[138:141]
	v_mfma_f32_16x16x32_bf16 v[126:129], v[50:53], v[212:215], v[126:129]
	v_mfma_f32_16x16x32_bf16 v[122:125], v[66:69], v[212:215], v[122:125]
	v_mfma_f32_16x16x32_bf16 v[110:113], v[50:53], v[220:223], v[110:113]
	v_mfma_f32_16x16x32_bf16 v[106:109], v[66:69], v[220:223], v[106:109]
	v_mfma_f32_16x16x32_bf16 v[94:97], v[50:53], v[228:231], v[94:97]
	v_mfma_f32_16x16x32_bf16 v[90:93], v[66:69], v[228:231], v[90:93]
	v_mfma_f32_16x16x32_bf16 v[142:145], v[54:57], v[208:211], v[142:145]
	v_mfma_f32_16x16x32_bf16 v[138:141], v[70:73], v[208:211], v[138:141]
	v_mfma_f32_16x16x32_bf16 v[126:129], v[54:57], v[216:219], v[126:129]
	v_mfma_f32_16x16x32_bf16 v[122:125], v[70:73], v[216:219], v[122:125]
	v_mfma_f32_16x16x32_bf16 v[110:113], v[54:57], v[224:227], v[110:113]
	v_mfma_f32_16x16x32_bf16 v[106:109], v[70:73], v[224:227], v[106:109]
	v_mfma_f32_16x16x32_bf16 v[94:97], v[54:57], v[232:235], v[94:97]
	v_mfma_f32_16x16x32_bf16 v[90:93], v[70:73], v[232:235], v[90:93]
	s_setprio 0
	s_setprio 1
	v_mfma_f32_16x16x32_bf16 v[134:137], v[146:149], v[192:195], v[134:137]
	v_mfma_f32_16x16x32_bf16 v[130:133], v[154:157], v[192:195], v[130:133]
	v_mfma_f32_16x16x32_bf16 v[118:121], v[146:149], v[212:215], v[118:121]
	v_mfma_f32_16x16x32_bf16 v[114:117], v[154:157], v[212:215], v[114:117]
	v_mfma_f32_16x16x32_bf16 v[102:105], v[146:149], v[220:223], v[102:105]
	v_mfma_f32_16x16x32_bf16 v[98:101], v[154:157], v[220:223], v[98:101]
	v_mfma_f32_16x16x32_bf16 v[86:89], v[146:149], v[228:231], v[86:89]
	v_mfma_f32_16x16x32_bf16 v[82:85], v[154:157], v[228:231], v[82:85]
	v_mfma_f32_16x16x32_bf16 v[134:137], v[150:153], v[208:211], v[134:137]
	v_mfma_f32_16x16x32_bf16 v[130:133], v[158:161], v[208:211], v[130:133]
	v_mfma_f32_16x16x32_bf16 v[118:121], v[150:153], v[216:219], v[118:121]
	v_mfma_f32_16x16x32_bf16 v[114:117], v[158:161], v[216:219], v[114:117]
	v_mfma_f32_16x16x32_bf16 v[102:105], v[150:153], v[224:227], v[102:105]
	v_mfma_f32_16x16x32_bf16 v[98:101], v[158:161], v[224:227], v[98:101]
	v_mfma_f32_16x16x32_bf16 v[86:89], v[150:153], v[232:235], v[86:89]
	v_mfma_f32_16x16x32_bf16 v[82:85], v[158:161], v[232:235], v[82:85]
	s_setprio 0
	s_barrier
	s_add_i32 s6, s11, s56
	v_lshl_add_u64 v[196:197], v[196:197], 0, s[34:35]
	s_mov_b32 m0, s6
	ds_read_b128 v[192:195], v204 offset:49152
	ds_read_b128 v[208:211], v204 offset:50176
	ds_read_b128 v[212:215], v204 offset:51200
	ds_read_b128 v[216:219], v204 offset:52224
	ds_read_b128 v[220:223], v204 offset:53248
	ds_read_b128 v[224:227], v204 offset:54272
	ds_read_b128 v[228:231], v204 offset:55296
	ds_read_b128 v[232:235], v204 offset:56320
	global_load_lds_dwordx4 v[196:197], off
	v_lshl_add_u64 v[196:197], v[236:237], 0, s[34:35]
	s_add_i32 m0, s6, 0x2000
	s_add_i32 s6, s46, s56
	global_load_lds_dwordx4 v[196:197], off
	v_lshl_add_u64 v[196:197], v[238:239], 0, s[34:35]
	s_mov_b32 m0, s6
	s_nop 0
	global_load_lds_dwordx4 v[196:197], off
	v_lshl_add_u64 v[196:197], v[240:241], 0, s[34:35]
	s_add_i32 m0, s6, 0x2000
	s_nop 0
	global_load_lds_dwordx4 v[196:197], off
	v_lshl_add_u64 v[196:197], v[242:243], 0, s[34:35]
	s_mov_b32 m0, s82
	s_nop 0
	global_load_lds_dwordx4 v[196:197], off
	v_lshl_add_u64 v[196:197], v[244:245], 0, s[34:35]
	s_mov_b32 m0, s83
	s_nop 0
	global_load_lds_dwordx4 v[196:197], off
	s_waitcnt vmcnt(8)
	s_waitcnt lgkmcnt(0)
	s_barrier
	s_setprio 1
	s_waitcnt lgkmcnt(0)
	v_mfma_f32_16x16x32_bf16 v[78:81], v[50:53], v[192:195], v[78:81]
	v_mfma_f32_16x16x32_bf16 v[74:77], v[66:69], v[192:195], v[74:77]
	v_mfma_f32_16x16x32_bf16 v[62:65], v[50:53], v[212:215], v[62:65]
	v_mfma_f32_16x16x32_bf16 v[58:61], v[66:69], v[212:215], v[58:61]
	v_mfma_f32_16x16x32_bf16 v[30:33], v[50:53], v[220:223], v[30:33]
	v_mfma_f32_16x16x32_bf16 v[26:29], v[66:69], v[220:223], v[26:29]
	v_mfma_f32_16x16x32_bf16 v[14:17], v[50:53], v[228:231], v[14:17]
	v_mfma_f32_16x16x32_bf16 v[10:13], v[66:69], v[228:231], v[10:13]
	v_mfma_f32_16x16x32_bf16 v[78:81], v[54:57], v[208:211], v[78:81]
	v_mfma_f32_16x16x32_bf16 v[74:77], v[70:73], v[208:211], v[74:77]
	v_mfma_f32_16x16x32_bf16 v[62:65], v[54:57], v[216:219], v[62:65]
	v_mfma_f32_16x16x32_bf16 v[58:61], v[70:73], v[216:219], v[58:61]
	v_mfma_f32_16x16x32_bf16 v[30:33], v[54:57], v[224:227], v[30:33]
	v_mfma_f32_16x16x32_bf16 v[26:29], v[70:73], v[224:227], v[26:29]
	v_mfma_f32_16x16x32_bf16 v[14:17], v[54:57], v[232:235], v[14:17]
	v_mfma_f32_16x16x32_bf16 v[10:13], v[70:73], v[232:235], v[10:13]
	s_setprio 0
	s_setprio 1
	v_mfma_f32_16x16x32_bf16 v[34:37], v[146:149], v[192:195], v[34:37]
	v_mfma_f32_16x16x32_bf16 v[70:73], v[150:153], v[208:211], v[34:37]
	v_mfma_f32_16x16x32_bf16 v[34:37], v[154:157], v[192:195], v[38:41]
	v_mfma_f32_16x16x32_bf16 v[66:69], v[158:161], v[208:211], v[34:37]
	v_mfma_f32_16x16x32_bf16 v[34:37], v[146:149], v[212:215], v[42:45]
	v_mfma_f32_16x16x32_bf16 v[54:57], v[150:153], v[216:219], v[34:37]
	v_mfma_f32_16x16x32_bf16 v[34:37], v[154:157], v[212:215], v[46:49]
	v_mfma_f32_16x16x32_bf16 v[22:25], v[146:149], v[220:223], v[22:25]
	v_mfma_f32_16x16x32_bf16 v[18:21], v[154:157], v[220:223], v[18:21]
	v_mfma_f32_16x16x32_bf16 v[6:9], v[146:149], v[228:231], v[6:9]
	v_mfma_f32_16x16x32_bf16 v[2:5], v[154:157], v[228:231], v[2:5]
	v_mfma_f32_16x16x32_bf16 v[50:53], v[158:161], v[216:219], v[34:37]
	v_mfma_f32_16x16x32_bf16 v[22:25], v[150:153], v[224:227], v[22:25]
	v_mfma_f32_16x16x32_bf16 v[18:21], v[158:161], v[224:227], v[18:21]
	v_mfma_f32_16x16x32_bf16 v[6:9], v[150:153], v[232:235], v[6:9]
	v_mfma_f32_16x16x32_bf16 v[2:5], v[158:161], v[232:235], v[2:5]
	s_setprio 0
	s_barrier
	s_add_u32 s4, s4, 0x100
	s_addc_u32 s5, s5, 0
	s_add_u32 s8, s8, 0x100
	s_addc_u32 s9, s9, 0
	s_cmp_ge_i32 s10, s85
	s_mov_b32 s6, s10
	s_cbranch_scc0 .LBB0_310

.LBB0_733:
	s_lshl_b32 s50, s80, 8
	s_add_i32 s50, s50, s70
	v_or_b32_e32 v160, s50, v162
	v_cmp_lt_i32_e32 vcc, s75, v160
	s_and_saveexec_b64 s[48:49], vcc
	s_xor_b64 s[48:49], exec, s[48:49]
	v_add_u32_e32 v154, 0xffff0000, v160
	v_mov_b32_e32 v155, v137
	v_lshlrev_b64 v[152:153], 12, v[154:155]
	v_lshrrev_b32_e32 v151, 5, v154
	v_lshl_add_u64 v[152:153], s[10:11], 0, v[152:153]
	v_add_u32_e32 v158, 32, v151
	v_mov_b32_e32 v161, v137
	s_or_saveexec_b64 s[48:49], s[48:49]
	s_ashr_i32 s51, s50, 11
	s_xor_b64 exec, exec, s[48:49]
	v_ashrrev_i32_e32 v161, 31, v160
	v_lshlrev_b64 v[152:153], 12, v[160:161]
	v_lshl_add_u64 v[152:153], s[8:9], 0, v[152:153]
	v_mov_b32_e32 v158, s51
	s_or_b64 exec, exec, s[48:49]
	v_lshl_or_b32 v178, s79, 8, v166
	v_lshl_add_u64 v[152:153], v[138:139], 2, v[152:153]
	v_ashrrev_i32_e32 v179, 31, v178
	v_lshl_add_u64 v[152:153], v[140:141], 2, v[152:153]
	v_lshl_add_u64 v[154:155], v[152:153], 0, v[136:137]
	v_lshlrev_b64 v[152:153], 2, v[178:179]
	v_lshl_add_u64 v[182:183], v[154:155], 0, v[152:153]
	v_add_co_u32_e32 v190, vcc, s71, v182
	v_add_u32_e32 v173, v165, v163
	s_nop 0
	v_addc_co_u32_e32 v191, vcc, 0, v183, vcc
	global_load_dwordx4 v[154:157], v[182:183], off nt
	global_load_dwordx4 v[174:177], v[190:191], off nt
	global_load_dwordx4 v[218:221], v[182:183], off offset:128 nt
	global_load_dwordx4 v[222:225], v[190:191], off offset:128 nt
	v_mov_b64_e32 v[182:183], s[28:29]
	v_mad_i64_i32 v[182:183], s[48:49], v158, s76, v[182:183]
	v_lshl_add_u64 v[182:183], v[182:183], 0, v[152:153]
	global_load_dwordx4 v[228:231], v[182:183], off
	global_load_dwordx4 v[232:235], v[182:183], off offset:16
	global_load_dwordx4 v[236:239], v[182:183], off offset:128
	global_load_dwordx4 v[240:243], v[182:183], off offset:144
	v_ashrrev_i32_e32 v159, 31, v158
	v_lshlrev_b64 v[216:217], 12, v[158:159]
	v_mov_b32_e32 v151, v137
	s_waitcnt vmcnt(6)
	ds_write_b128 v171, v[154:157]
	ds_write_b128 v171, v[174:177] offset:1152
	s_waitcnt lgkmcnt(0)
	ds_read_b128 v[174:177], v172
	ds_read_b128 v[186:189], v172 offset:16
	s_waitcnt lgkmcnt(0)
	s_nop 0
	v_lshlrev_b64 v[158:159], 1, v[178:179]
	v_lshl_add_u64 v[178:179], s[34:35], 0, v[216:217]
	v_lshl_add_u64 v[178:179], v[178:179], 0, v[152:153]
	s_waitcnt vmcnt(2)
	ds_write_b128 v171, v[218:221]
	ds_write_b128 v171, v[222:225] offset:1152
	s_waitcnt lgkmcnt(0)
	ds_read_b128 v[190:193], v172
	ds_read_b128 v[202:205], v172 offset:16
	s_waitcnt lgkmcnt(0)
	s_waitcnt lgkmcnt(0)
	v_pk_fma_f32 v[196:197], v[122:123], v[230:231], v[176:177]
	v_pk_fma_f32 v[194:195], v[120:121], v[228:229], v[174:175]
	v_pk_fma_f32 v[188:189], v[126:127], v[234:235], v[188:189]
	v_pk_fma_f32 v[186:187], v[124:125], v[232:233], v[186:187]
	v_cvt_pk_bf16_f32 v120, v194, v195
	v_cvt_pk_bf16_f32 v121, v196, v197
	v_cvt_pk_bf16_f32 v122, v186, v187
	v_cvt_pk_bf16_f32 v123, v188, v189
	v_lshlrev_b64 v[182:183], 11, v[160:161]
	ds_write_b128 v173, v[120:123]
	v_lshl_add_u64 v[214:215], s[38:39], 0, v[182:183]
	v_lshlrev_b64 v[156:157], 1, v[138:139]
	v_lshl_add_u64 v[214:215], v[214:215], 0, v[158:159]
	v_lshlrev_b64 v[154:155], 1, v[140:141]
	v_lshl_add_u64 v[214:215], v[214:215], 0, v[156:157]
	v_lshl_add_u64 v[214:215], v[214:215], 0, v[154:155]
	v_lshl_add_u64 v[214:215], v[214:215], 0, v[150:151]
	v_add_co_u32_e32 v120, vcc, s62, v214
	s_waitcnt vmcnt(1)
	v_pk_fma_f32 v[192:193], v[118:119], v[238:239], v[192:193]
	v_pk_fma_f32 v[190:191], v[116:117], v[236:237], v[190:191]
	s_waitcnt vmcnt(0)
	v_pk_fma_f32 v[198:199], v[114:115], v[242:243], v[204:205]
	v_pk_fma_f32 v[200:201], v[112:113], v[240:241], v[202:203]
	v_cvt_pk_bf16_f32 v112, v190, v191
	v_cvt_pk_bf16_f32 v113, v192, v193
	v_cvt_pk_bf16_f32 v114, v200, v201
	v_cvt_pk_bf16_f32 v115, v198, v199
	ds_write_b128 v173, v[112:115] offset:64
	s_waitcnt lgkmcnt(0)
	ds_read_b128 v[112:115], v171
	ds_read_b128 v[116:119], v171 offset:1152
	v_addc_co_u32_e32 v121, vcc, 0, v215, vcc
	s_waitcnt lgkmcnt(1)
	global_store_dwordx4 v[214:215], v[112:115], off
	s_waitcnt lgkmcnt(0)
	global_store_dwordx4 v[120:121], v[116:119], off
	s_waitcnt lgkmcnt(0)
	global_load_dwordx4 v[112:115], v[178:179], off
	global_load_dwordx4 v[120:123], v[178:179], off offset:16
	global_load_dwordx4 v[124:127], v[178:179], off offset:128
	global_load_dwordx4 v[174:177], v[178:179], off offset:144
	v_and_b32_e32 v119, 64, v170
	v_xor_b32_e32 v118, 16, v170
	v_lshl_add_u64 v[116:117], s[30:31], 0, v[182:183]
	v_add_u32_e32 v119, 64, v119
	v_xor_b32_e32 v178, 32, v170
	v_cmp_lt_i32_e32 vcc, v118, v119
	v_lshl_add_u64 v[116:117], v[116:117], 0, v[158:159]
	v_lshl_add_u64 v[116:117], v[116:117], 0, v[156:157]
	v_cndmask_b32_e32 v118, v170, v118, vcc
	v_cmp_lt_i32_e32 vcc, v178, v119
	v_lshl_add_u64 v[116:117], v[116:117], 0, v[154:155]
	v_lshlrev_b32_e32 v119, 2, v118
	v_cndmask_b32_e32 v178, v170, v178, vcc
	v_lshlrev_b32_e32 v118, 2, v178
	v_lshl_add_u64 v[178:179], v[116:117], 0, v[150:151]
	v_mul_f32_e32 v116, v195, v195
	v_mul_f32_e32 v117, v197, v197
	v_mul_f32_e32 v151, v187, v187
	v_mul_f32_e32 v182, v189, v189
	v_fmac_f32_e32 v116, v194, v194
	v_fmac_f32_e32 v117, v196, v196
	v_fmac_f32_e32 v151, v186, v186
	v_fmac_f32_e32 v182, v188, v188
	v_add_f32_e32 v116, v116, v117
	v_add_f32_e32 v117, v151, v182
	v_add_f32_e32 v116, v116, v117
	v_mul_f32_e32 v117, v191, v191
	v_mul_f32_e32 v151, v193, v193
	v_mul_f32_e32 v182, v201, v201
	v_mul_f32_e32 v183, v199, v199
	v_fmac_f32_e32 v117, v190, v190
	v_fmac_f32_e32 v151, v192, v192
	v_fmac_f32_e32 v182, v200, v200
	v_fmac_f32_e32 v183, v198, v198
	v_add_f32_e32 v117, v117, v151
	v_add_f32_e32 v151, v182, v183
	v_add_f32_e32 v117, v117, v151
	v_add_f32_e32 v151, v116, v117
	ds_bpermute_b32 v182, v119, v151
	s_waitcnt vmcnt(3)
	v_pk_mul_f32 v[114:115], v[196:197], v[114:115]
	v_pk_mul_f32 v[112:113], v[194:195], v[112:113]
	s_waitcnt vmcnt(2)
	v_pk_mul_f32 v[116:117], v[188:189], v[122:123]
	v_pk_mul_f32 v[120:121], v[186:187], v[120:121]
	s_waitcnt vmcnt(1)
	v_pk_mul_f32 v[122:123], v[192:193], v[126:127]
	v_pk_mul_f32 v[124:125], v[190:191], v[124:125]
	s_waitcnt vmcnt(0)
	v_pk_mul_f32 v[126:127], v[198:199], v[176:177]
	v_pk_mul_f32 v[174:175], v[200:201], v[174:175]
	v_cvt_pk_bf16_f32 v112, v112, v113
	v_cvt_pk_bf16_f32 v113, v114, v115
	v_cvt_pk_bf16_f32 v114, v120, v121
	v_cvt_pk_bf16_f32 v115, v116, v117
	v_cvt_pk_bf16_f32 v120, v124, v125
	v_cvt_pk_bf16_f32 v121, v122, v123
	v_cvt_pk_bf16_f32 v122, v174, v175
	v_cvt_pk_bf16_f32 v123, v126, v127
	ds_write_b128 v173, v[112:115]
	ds_write_b128 v173, v[120:123] offset:64
	s_waitcnt lgkmcnt(0)
	ds_read_b128 v[114:117], v171
	ds_read_b128 v[120:123], v171 offset:1152
	s_waitcnt lgkmcnt(4)
	v_add_f32_e32 v112, v151, v182
	v_add_co_u32_e32 v124, vcc, s62, v178
	ds_bpermute_b32 v113, v118, v112
	s_nop 0
	v_addc_co_u32_e32 v125, vcc, 0, v179, vcc
	s_waitcnt lgkmcnt(2)
	global_store_dwordx4 v[178:179], v[114:117], off
	s_waitcnt lgkmcnt(1)
	global_store_dwordx4 v[124:125], v[120:123], off
	s_waitcnt lgkmcnt(0)
	s_and_saveexec_b64 s[48:49], s[2:3]
	s_cbranch_execz .LBB0_739
	v_lshl_add_u64 v[114:115], v[160:161], 2, s[36:37]
	s_waitcnt lgkmcnt(0)
	v_add_f32_e32 v112, v112, v113
	global_atomic_add_f32 v[114:115], v112, off
.LBB0_739:
	s_or_b64 exec, exec, s[48:49]
	s_waitcnt lgkmcnt(0)
	v_or_b32_e32 v112, 16, v160
	v_cmp_lt_i32_e32 vcc, s75, v112
	s_and_saveexec_b64 s[48:49], vcc
	s_xor_b64 s[48:49], exec, s[48:49]
	v_add_u32_e32 v114, 0xffff0010, v160
	v_mov_b32_e32 v115, v137
	v_lshlrev_b64 v[116:117], 12, v[114:115]
	v_lshrrev_b32_e32 v113, 5, v114
	v_lshl_add_u64 v[116:117], s[10:11], 0, v[116:117]
	v_add_u32_e32 v114, 32, v113
	v_mov_b32_e32 v113, v137
	s_andn2_saveexec_b64 s[48:49], s[48:49]
	v_ashrrev_i32_e32 v113, 31, v112
	v_lshlrev_b64 v[114:115], 12, v[112:113]
	v_lshl_add_u64 v[116:117], s[8:9], 0, v[114:115]
	v_mov_b32_e32 v114, s51
	s_or_b64 exec, exec, s[48:49]
	v_lshl_add_u64 v[116:117], v[138:139], 2, v[116:117]
	v_lshl_add_u64 v[116:117], v[140:141], 2, v[116:117]
	v_lshl_add_u64 v[116:117], v[116:117], 0, v[136:137]
	v_lshl_add_u64 v[116:117], v[116:117], 0, v[152:153]
	v_add_co_u32_e32 v178, vcc, 0x8000, v116
	v_mov_b32_e32 v151, v137
	s_nop 0
	v_addc_co_u32_e32 v179, vcc, 0, v117, vcc
	global_load_dwordx4 v[120:123], v[116:117], off nt
	global_load_dwordx4 v[124:127], v[178:179], off nt
	global_load_dwordx4 v[218:221], v[116:117], off offset:128 nt
	global_load_dwordx4 v[222:225], v[178:179], off offset:128 nt
	v_mov_b64_e32 v[116:117], s[28:29]
	v_mad_i64_i32 v[116:117], s[48:49], v114, s76, v[116:117]
	v_lshl_add_u64 v[116:117], v[116:117], 0, v[152:153]
	global_load_dwordx4 v[228:231], v[116:117], off
	global_load_dwordx4 v[232:235], v[116:117], off offset:16
	global_load_dwordx4 v[236:239], v[116:117], off offset:128
	global_load_dwordx4 v[240:243], v[116:117], off offset:144
	v_ashrrev_i32_e32 v115, 31, v114
	s_waitcnt vmcnt(7)
	ds_write_b128 v171, v[120:123]
	s_waitcnt vmcnt(6)
	ds_write_b128 v171, v[124:127] offset:1152
	s_waitcnt lgkmcnt(0)
	ds_read_b128 v[120:123], v172
	ds_read_b128 v[124:127], v172 offset:16
	s_waitcnt lgkmcnt(0)
	v_lshlrev_b64 v[114:115], 12, v[114:115]
	v_lshl_add_u64 v[114:115], s[34:35], 0, v[114:115]
	v_lshl_add_u64 v[114:115], v[114:115], 0, v[152:153]
	s_waitcnt vmcnt(5)
	ds_write_b128 v171, v[218:221]
	s_waitcnt vmcnt(4)
	ds_write_b128 v171, v[222:225] offset:1152
	s_waitcnt lgkmcnt(0)
	ds_read_b128 v[174:177], v172
	ds_read_b128 v[186:189], v172 offset:16
	s_waitcnt lgkmcnt(0)
	s_waitcnt vmcnt(3) lgkmcnt(5)
	v_pk_fma_f32 v[122:123], v[110:111], v[230:231], v[122:123]
	v_pk_fma_f32 v[120:121], v[108:109], v[228:229], v[120:121]
	s_waitcnt vmcnt(2) lgkmcnt(4)
	v_pk_fma_f32 v[126:127], v[106:107], v[234:235], v[126:127]
	v_pk_fma_f32 v[124:125], v[104:105], v[232:233], v[124:125]
	v_cvt_pk_bf16_f32 v104, v120, v121
	v_cvt_pk_bf16_f32 v105, v122, v123
	v_cvt_pk_bf16_f32 v106, v124, v125
	v_cvt_pk_bf16_f32 v107, v126, v127
	v_lshlrev_b64 v[116:117], 11, v[112:113]
	ds_write_b128 v173, v[104:107]
	v_lshl_add_u64 v[178:179], s[38:39], 0, v[116:117]
	v_lshl_add_u64 v[178:179], v[178:179], 0, v[158:159]
	v_lshl_add_u64 v[178:179], v[178:179], 0, v[156:157]
	v_lshl_add_u64 v[178:179], v[178:179], 0, v[154:155]
	v_lshl_add_u64 v[178:179], v[178:179], 0, v[150:151]
	v_add_co_u32_e32 v104, vcc, s62, v178
	v_mul_f32_e32 v161, v127, v127
	s_nop 0
	v_addc_co_u32_e32 v105, vcc, 0, v179, vcc
	v_fmac_f32_e32 v161, v126, v126
	s_waitcnt vmcnt(1) lgkmcnt(2)
	v_pk_fma_f32 v[176:177], v[102:103], v[238:239], v[176:177]
	v_pk_fma_f32 v[174:175], v[100:101], v[236:237], v[174:175]
	s_waitcnt vmcnt(0) lgkmcnt(1)
	v_pk_fma_f32 v[182:183], v[98:99], v[242:243], v[188:189]
	v_pk_fma_f32 v[186:187], v[96:97], v[240:241], v[186:187]
	v_cvt_pk_bf16_f32 v96, v174, v175
	v_cvt_pk_bf16_f32 v97, v176, v177
	v_cvt_pk_bf16_f32 v98, v186, v187
	v_cvt_pk_bf16_f32 v99, v182, v183
	ds_write_b128 v173, v[96:99] offset:64
	s_waitcnt lgkmcnt(0)
	ds_read_b128 v[96:99], v171
	ds_read_b128 v[100:103], v171 offset:1152
	s_waitcnt lgkmcnt(1)
	global_store_dwordx4 v[178:179], v[96:99], off
	s_waitcnt lgkmcnt(0)
	global_store_dwordx4 v[104:105], v[100:103], off
	s_waitcnt lgkmcnt(0)
	global_load_dwordx4 v[96:99], v[114:115], off
	global_load_dwordx4 v[100:103], v[114:115], off offset:16
	global_load_dwordx4 v[104:107], v[114:115], off offset:128
	global_load_dwordx4 v[108:111], v[114:115], off offset:144
	v_lshl_add_u64 v[114:115], s[30:31], 0, v[116:117]
	v_lshl_add_u64 v[114:115], v[114:115], 0, v[158:159]
	v_lshl_add_u64 v[114:115], v[114:115], 0, v[156:157]
	v_lshl_add_u64 v[114:115], v[114:115], 0, v[154:155]
	v_lshl_add_u64 v[114:115], v[114:115], 0, v[150:151]
	v_mul_f32_e32 v116, v121, v121
	v_mul_f32_e32 v117, v123, v123
	v_mul_f32_e32 v151, v125, v125
	v_fmac_f32_e32 v116, v120, v120
	v_fmac_f32_e32 v117, v122, v122
	v_fmac_f32_e32 v151, v124, v124
	v_add_f32_e32 v116, v116, v117
	v_add_f32_e32 v117, v151, v161
	v_add_f32_e32 v116, v116, v117
	v_mul_f32_e32 v117, v175, v175
	v_mul_f32_e32 v151, v177, v177
	v_mul_f32_e32 v161, v187, v187
	v_mul_f32_e32 v178, v183, v183
	v_fmac_f32_e32 v117, v174, v174
	v_fmac_f32_e32 v151, v176, v176
	v_fmac_f32_e32 v161, v186, v186
	v_fmac_f32_e32 v178, v182, v182
	v_add_f32_e32 v117, v117, v151
	v_add_f32_e32 v151, v161, v178
	v_add_f32_e32 v117, v117, v151
	v_add_f32_e32 v116, v116, v117
	ds_bpermute_b32 v117, v119, v116
	s_waitcnt vmcnt(3)
	v_pk_mul_f32 v[98:99], v[122:123], v[98:99]
	v_pk_mul_f32 v[96:97], v[120:121], v[96:97]
	s_waitcnt vmcnt(2)
	v_pk_mul_f32 v[102:103], v[126:127], v[102:103]
	v_pk_mul_f32 v[100:101], v[124:125], v[100:101]
	s_waitcnt vmcnt(1)
	v_pk_mul_f32 v[106:107], v[176:177], v[106:107]
	v_pk_mul_f32 v[104:105], v[174:175], v[104:105]
	s_waitcnt vmcnt(0)
	v_pk_mul_f32 v[110:111], v[182:183], v[110:111]
	v_pk_mul_f32 v[108:109], v[186:187], v[108:109]
	v_cvt_pk_bf16_f32 v96, v96, v97
	v_cvt_pk_bf16_f32 v97, v98, v99
	v_cvt_pk_bf16_f32 v98, v100, v101
	v_cvt_pk_bf16_f32 v99, v102, v103
	v_cvt_pk_bf16_f32 v100, v104, v105
	v_cvt_pk_bf16_f32 v101, v106, v107
	v_cvt_pk_bf16_f32 v102, v108, v109
	v_cvt_pk_bf16_f32 v103, v110, v111
	ds_write_b128 v173, v[96:99]
	ds_write_b128 v173, v[100:103] offset:64
	s_waitcnt lgkmcnt(0)
	ds_read_b128 v[98:101], v171
	ds_read_b128 v[102:105], v171 offset:1152
	s_waitcnt lgkmcnt(4)
	v_add_f32_e32 v96, v116, v117
	v_add_co_u32_e32 v106, vcc, s62, v114
	ds_bpermute_b32 v97, v118, v96
	s_nop 0
	v_addc_co_u32_e32 v107, vcc, 0, v115, vcc
	s_waitcnt lgkmcnt(2)
	global_store_dwordx4 v[114:115], v[98:101], off
	s_waitcnt lgkmcnt(1)
	global_store_dwordx4 v[106:107], v[102:105], off
	s_waitcnt lgkmcnt(0)
	s_and_saveexec_b64 s[48:49], s[2:3]
	s_cbranch_execz .LBB0_745
	v_lshl_add_u64 v[98:99], v[112:113], 2, s[36:37]
	s_waitcnt lgkmcnt(0)
	v_add_f32_e32 v96, v96, v97
	global_atomic_add_f32 v[98:99], v96, off
.LBB0_745:
	s_or_b64 exec, exec, s[48:49]
	s_waitcnt lgkmcnt(0)
	v_or_b32_e32 v96, 32, v160
	v_cmp_lt_i32_e32 vcc, s75, v96
	s_and_saveexec_b64 s[48:49], vcc
	s_xor_b64 s[48:49], exec, s[48:49]
	v_add_u32_e32 v98, 0xffff0020, v160
	v_mov_b32_e32 v99, v137
	v_lshlrev_b64 v[100:101], 12, v[98:99]
	v_lshrrev_b32_e32 v97, 5, v98
	v_lshl_add_u64 v[100:101], s[10:11], 0, v[100:101]
	v_add_u32_e32 v98, 32, v97
	v_mov_b32_e32 v97, v137
	s_andn2_saveexec_b64 s[48:49], s[48:49]
	v_ashrrev_i32_e32 v97, 31, v96
	v_lshlrev_b64 v[98:99], 12, v[96:97]
	v_lshl_add_u64 v[100:101], s[8:9], 0, v[98:99]
	v_mov_b32_e32 v98, s51
	s_or_b64 exec, exec, s[48:49]
	v_lshl_add_u64 v[100:101], v[138:139], 2, v[100:101]
	v_lshl_add_u64 v[100:101], v[140:141], 2, v[100:101]
	v_lshl_add_u64 v[100:101], v[100:101], 0, v[136:137]
	v_lshl_add_u64 v[108:109], v[100:101], 0, v[152:153]
	v_add_co_u32_e32 v112, vcc, 0x8000, v108
	v_mov_b64_e32 v[116:117], s[28:29]
	s_nop 0
	v_addc_co_u32_e32 v113, vcc, 0, v109, vcc
	global_load_dwordx4 v[100:103], v[108:109], off nt
	global_load_dwordx4 v[104:107], v[112:113], off nt
	v_mad_i64_i32 v[116:117], s[48:49], v98, s76, v[116:117]
	v_lshl_add_u64 v[116:117], v[116:117], 0, v[152:153]
	global_load_dwordx4 v[218:221], v[108:109], off offset:128 nt
	global_load_dwordx4 v[222:225], v[112:113], off offset:128 nt
	global_load_dwordx4 v[228:231], v[116:117], off
	global_load_dwordx4 v[232:235], v[116:117], off offset:16
	global_load_dwordx4 v[236:239], v[116:117], off offset:128
	global_load_dwordx4 v[240:243], v[116:117], off offset:144
	v_mov_b32_e32 v151, v137
	v_ashrrev_i32_e32 v99, 31, v98
	v_lshlrev_b64 v[98:99], 12, v[98:99]
	v_lshl_add_u64 v[98:99], s[34:35], 0, v[98:99]
	v_lshl_add_u64 v[98:99], v[98:99], 0, v[152:153]
	s_waitcnt vmcnt(7)
	ds_write_b128 v171, v[100:103]
	s_waitcnt vmcnt(6)
	ds_write_b128 v171, v[104:107] offset:1152
	s_waitcnt lgkmcnt(0)
	ds_read_b128 v[100:103], v172
	ds_read_b128 v[104:107], v172 offset:16
	s_waitcnt lgkmcnt(0)
	s_nop 0
	s_nop 0
	s_waitcnt vmcnt(5)
	ds_write_b128 v171, v[218:221]
	s_waitcnt vmcnt(4)
	ds_write_b128 v171, v[222:225] offset:1152
	s_waitcnt lgkmcnt(0)
	ds_read_b128 v[108:111], v172
	ds_read_b128 v[112:115], v172 offset:16
	s_waitcnt lgkmcnt(0)
	s_waitcnt vmcnt(3) lgkmcnt(5)
	v_pk_fma_f32 v[102:103], v[94:95], v[230:231], v[102:103]
	v_pk_fma_f32 v[100:101], v[92:93], v[228:229], v[100:101]
	s_waitcnt vmcnt(2) lgkmcnt(4)
	v_pk_fma_f32 v[106:107], v[90:91], v[234:235], v[106:107]
	v_pk_fma_f32 v[104:105], v[88:89], v[232:233], v[104:105]
	v_cvt_pk_bf16_f32 v88, v100, v101
	v_cvt_pk_bf16_f32 v89, v102, v103
	v_cvt_pk_bf16_f32 v90, v104, v105
	v_cvt_pk_bf16_f32 v91, v106, v107
	v_lshlrev_b64 v[116:117], 11, v[96:97]
	ds_write_b128 v173, v[88:91]
	v_lshl_add_u64 v[178:179], s[38:39], 0, v[116:117]
	v_lshl_add_u64 v[178:179], v[178:179], 0, v[158:159]
	v_lshl_add_u64 v[178:179], v[178:179], 0, v[156:157]
	v_lshl_add_u64 v[178:179], v[178:179], 0, v[154:155]
	v_lshl_add_u64 v[178:179], v[178:179], 0, v[150:151]
	v_add_co_u32_e32 v88, vcc, s62, v178
	v_mul_f32_e32 v120, v105, v105
	s_nop 0
	v_addc_co_u32_e32 v89, vcc, 0, v179, vcc
	v_mul_f32_e32 v121, v107, v107
	v_fmac_f32_e32 v120, v104, v104
	v_fmac_f32_e32 v121, v106, v106
	s_waitcnt vmcnt(1) lgkmcnt(2)
	v_pk_fma_f32 v[110:111], v[86:87], v[238:239], v[110:111]
	v_pk_fma_f32 v[108:109], v[84:85], v[236:237], v[108:109]
	s_waitcnt vmcnt(0) lgkmcnt(1)
	v_pk_fma_f32 v[114:115], v[82:83], v[242:243], v[114:115]
	v_pk_fma_f32 v[112:113], v[80:81], v[240:241], v[112:113]
	v_cvt_pk_bf16_f32 v80, v108, v109
	v_cvt_pk_bf16_f32 v81, v110, v111
	v_cvt_pk_bf16_f32 v82, v112, v113
	v_cvt_pk_bf16_f32 v83, v114, v115
	ds_write_b128 v173, v[80:83] offset:64
	s_waitcnt lgkmcnt(0)
	ds_read_b128 v[80:83], v171
	ds_read_b128 v[84:87], v171 offset:1152
	s_waitcnt lgkmcnt(1)
	global_store_dwordx4 v[178:179], v[80:83], off
	s_waitcnt lgkmcnt(0)
	global_store_dwordx4 v[88:89], v[84:87], off
	s_waitcnt lgkmcnt(0)
	global_load_dwordx4 v[80:83], v[98:99], off
	global_load_dwordx4 v[84:87], v[98:99], off offset:16
	global_load_dwordx4 v[88:91], v[98:99], off offset:128
	global_load_dwordx4 v[92:95], v[98:99], off offset:144
	v_lshl_add_u64 v[98:99], s[30:31], 0, v[116:117]
	v_mul_f32_e32 v116, v101, v101
	v_mul_f32_e32 v117, v103, v103
	v_fmac_f32_e32 v116, v100, v100
	v_fmac_f32_e32 v117, v102, v102
	v_add_f32_e32 v116, v116, v117
	v_add_f32_e32 v117, v120, v121
	v_add_f32_e32 v116, v116, v117
	v_mul_f32_e32 v117, v109, v109
	v_mul_f32_e32 v120, v111, v111
	v_mul_f32_e32 v121, v113, v113
	v_mul_f32_e32 v122, v115, v115
	v_fmac_f32_e32 v117, v108, v108
	v_fmac_f32_e32 v120, v110, v110
	v_fmac_f32_e32 v121, v112, v112
	v_fmac_f32_e32 v122, v114, v114
	v_add_f32_e32 v117, v117, v120
	v_add_f32_e32 v120, v121, v122
	v_add_f32_e32 v117, v117, v120
	v_add_f32_e32 v116, v116, v117
	ds_bpermute_b32 v117, v119, v116
	v_lshl_add_u64 v[98:99], v[98:99], 0, v[158:159]
	v_lshl_add_u64 v[98:99], v[98:99], 0, v[156:157]
	v_lshl_add_u64 v[98:99], v[98:99], 0, v[154:155]
	v_lshl_add_u64 v[98:99], v[98:99], 0, v[150:151]
	s_waitcnt vmcnt(3)
	v_pk_mul_f32 v[82:83], v[102:103], v[82:83]
	v_pk_mul_f32 v[80:81], v[100:101], v[80:81]
	s_waitcnt vmcnt(2)
	v_pk_mul_f32 v[86:87], v[106:107], v[86:87]
	v_pk_mul_f32 v[84:85], v[104:105], v[84:85]
	s_waitcnt vmcnt(1)
	v_pk_mul_f32 v[90:91], v[110:111], v[90:91]
	v_pk_mul_f32 v[88:89], v[108:109], v[88:89]
	s_waitcnt vmcnt(0)
	v_pk_mul_f32 v[94:95], v[114:115], v[94:95]
	v_pk_mul_f32 v[92:93], v[112:113], v[92:93]
	v_cvt_pk_bf16_f32 v80, v80, v81
	v_cvt_pk_bf16_f32 v81, v82, v83
	v_cvt_pk_bf16_f32 v82, v84, v85
	v_cvt_pk_bf16_f32 v83, v86, v87
	v_cvt_pk_bf16_f32 v84, v88, v89
	v_cvt_pk_bf16_f32 v85, v90, v91
	v_cvt_pk_bf16_f32 v86, v92, v93
	v_cvt_pk_bf16_f32 v87, v94, v95
	ds_write_b128 v173, v[80:83]
	ds_write_b128 v173, v[84:87] offset:64
	s_waitcnt lgkmcnt(0)
	ds_read_b128 v[82:85], v171
	ds_read_b128 v[86:89], v171 offset:1152
	s_waitcnt lgkmcnt(4)
	v_add_f32_e32 v80, v116, v117
	v_add_co_u32_e32 v90, vcc, s62, v98
	ds_bpermute_b32 v81, v118, v80
	s_nop 0
	v_addc_co_u32_e32 v91, vcc, 0, v99, vcc
	s_waitcnt lgkmcnt(2)
	global_store_dwordx4 v[98:99], v[82:85], off
	s_waitcnt lgkmcnt(1)
	global_store_dwordx4 v[90:91], v[86:89], off
	s_waitcnt lgkmcnt(0)
	s_and_saveexec_b64 s[48:49], s[2:3]
	s_cbranch_execz .LBB0_751
	v_lshl_add_u64 v[82:83], v[96:97], 2, s[36:37]
	s_waitcnt lgkmcnt(0)
	v_add_f32_e32 v80, v80, v81
	global_atomic_add_f32 v[82:83], v80, off
.LBB0_751:
	s_or_b64 exec, exec, s[48:49]
	s_waitcnt lgkmcnt(0)
	v_or_b32_e32 v80, 48, v160
	v_cmp_lt_i32_e32 vcc, s75, v80
	s_and_saveexec_b64 s[48:49], vcc
	s_xor_b64 s[48:49], exec, s[48:49]
	v_add_u32_e32 v82, 0xffff0030, v160
	v_mov_b32_e32 v83, v137
	v_lshlrev_b64 v[84:85], 12, v[82:83]
	v_lshrrev_b32_e32 v81, 5, v82
	v_lshl_add_u64 v[84:85], s[10:11], 0, v[84:85]
	v_add_u32_e32 v82, 32, v81
	v_mov_b32_e32 v81, v137
	s_andn2_saveexec_b64 s[48:49], s[48:49]
	v_ashrrev_i32_e32 v81, 31, v80
	v_lshlrev_b64 v[82:83], 12, v[80:81]
	v_lshl_add_u64 v[84:85], s[8:9], 0, v[82:83]
	v_mov_b32_e32 v82, s51
	s_or_b64 exec, exec, s[48:49]
	v_lshl_add_u64 v[84:85], v[138:139], 2, v[84:85]
	v_lshl_add_u64 v[84:85], v[140:141], 2, v[84:85]
	v_lshl_add_u64 v[84:85], v[84:85], 0, v[136:137]
	v_lshl_add_u64 v[92:93], v[84:85], 0, v[152:153]
	v_add_co_u32_e32 v96, vcc, 0x8000, v92
	v_mov_b64_e32 v[100:101], s[28:29]
	s_nop 0
	v_addc_co_u32_e32 v97, vcc, 0, v93, vcc
	global_load_dwordx4 v[84:87], v[92:93], off nt
	global_load_dwordx4 v[88:91], v[96:97], off nt
	v_mad_i64_i32 v[100:101], s[48:49], v82, s76, v[100:101]
	v_lshl_add_u64 v[112:113], v[100:101], 0, v[152:153]
	global_load_dwordx4 v[218:221], v[92:93], off offset:128 nt
	global_load_dwordx4 v[222:225], v[96:97], off offset:128 nt
	global_load_dwordx4 v[228:231], v[112:113], off
	global_load_dwordx4 v[232:235], v[112:113], off offset:16
	global_load_dwordx4 v[236:239], v[112:113], off offset:128
	global_load_dwordx4 v[240:243], v[112:113], off offset:144
	v_lshlrev_b64 v[116:117], 11, v[80:81]
	v_lshl_add_u64 v[120:121], s[38:39], 0, v[116:117]
	v_lshl_add_u64 v[120:121], v[120:121], 0, v[158:159]
	v_lshl_add_u64 v[120:121], v[120:121], 0, v[156:157]
	v_mov_b32_e32 v151, v137
	v_lshl_add_u64 v[120:121], v[120:121], 0, v[154:155]
	v_ashrrev_i32_e32 v83, 31, v82
	v_lshl_add_u64 v[120:121], v[120:121], 0, v[150:151]
	v_lshlrev_b64 v[82:83], 12, v[82:83]
	v_lshl_add_u64 v[82:83], s[34:35], 0, v[82:83]
	v_lshl_add_u64 v[82:83], v[82:83], 0, v[152:153]
	s_waitcnt vmcnt(7)
	ds_write_b128 v171, v[84:87]
	s_waitcnt vmcnt(6)
	ds_write_b128 v171, v[88:91] offset:1152
	s_waitcnt lgkmcnt(0)
	ds_read_b128 v[84:87], v172
	ds_read_b128 v[88:91], v172 offset:16
	s_waitcnt lgkmcnt(0)
	s_nop 0
	s_nop 0
	s_waitcnt vmcnt(5)
	ds_write_b128 v171, v[218:221]
	s_waitcnt vmcnt(4)
	ds_write_b128 v171, v[222:225] offset:1152
	s_waitcnt lgkmcnt(0)
	ds_read_b128 v[92:95], v172
	ds_read_b128 v[96:99], v172 offset:16
	s_waitcnt lgkmcnt(0)
	s_nop 0
	s_waitcnt vmcnt(3) lgkmcnt(5)
	v_pk_fma_f32 v[86:87], v[78:79], v[230:231], v[86:87]
	v_pk_fma_f32 v[84:85], v[76:77], v[228:229], v[84:85]
	s_waitcnt vmcnt(2) lgkmcnt(4)
	v_pk_fma_f32 v[90:91], v[74:75], v[234:235], v[90:91]
	v_pk_fma_f32 v[88:89], v[72:73], v[232:233], v[88:89]
	v_cvt_pk_bf16_f32 v72, v84, v85
	v_cvt_pk_bf16_f32 v73, v86, v87
	v_cvt_pk_bf16_f32 v74, v88, v89
	v_cvt_pk_bf16_f32 v75, v90, v91
	ds_write_b128 v173, v[72:75]
	v_add_co_u32_e32 v72, vcc, s62, v120
	v_mul_f32_e32 v100, v85, v85
	s_nop 0
	v_addc_co_u32_e32 v73, vcc, 0, v121, vcc
	v_mul_f32_e32 v101, v87, v87
	v_mul_f32_e32 v102, v89, v89
	v_mul_f32_e32 v103, v91, v91
	v_fmac_f32_e32 v100, v84, v84
	v_fmac_f32_e32 v101, v86, v86
	v_fmac_f32_e32 v102, v88, v88
	v_fmac_f32_e32 v103, v90, v90
	v_add_f32_e32 v100, v100, v101
	v_add_f32_e32 v101, v102, v103
	v_add_f32_e32 v100, v100, v101
	s_waitcnt vmcnt(1) lgkmcnt(2)
	v_pk_fma_f32 v[94:95], v[70:71], v[238:239], v[94:95]
	v_pk_fma_f32 v[92:93], v[68:69], v[236:237], v[92:93]
	s_waitcnt vmcnt(0) lgkmcnt(1)
	v_pk_fma_f32 v[98:99], v[66:67], v[242:243], v[98:99]
	v_pk_fma_f32 v[96:97], v[64:65], v[240:241], v[96:97]
	v_cvt_pk_bf16_f32 v64, v92, v93
	v_cvt_pk_bf16_f32 v65, v94, v95
	v_cvt_pk_bf16_f32 v66, v96, v97
	v_cvt_pk_bf16_f32 v67, v98, v99
	ds_write_b128 v173, v[64:67] offset:64
	s_waitcnt lgkmcnt(0)
	ds_read_b128 v[64:67], v171
	ds_read_b128 v[68:71], v171 offset:1152
	s_waitcnt lgkmcnt(1)
	global_store_dwordx4 v[120:121], v[64:67], off
	s_waitcnt lgkmcnt(0)
	global_store_dwordx4 v[72:73], v[68:71], off
	s_waitcnt lgkmcnt(0)
	global_load_dwordx4 v[64:67], v[82:83], off
	global_load_dwordx4 v[68:71], v[82:83], off offset:16
	global_load_dwordx4 v[72:75], v[82:83], off offset:128
	global_load_dwordx4 v[76:79], v[82:83], off offset:144
	v_mul_f32_e32 v101, v93, v93
	v_mul_f32_e32 v102, v95, v95
	v_mul_f32_e32 v103, v97, v97
	v_mul_f32_e32 v104, v99, v99
	v_fmac_f32_e32 v101, v92, v92
	v_fmac_f32_e32 v102, v94, v94
	v_fmac_f32_e32 v103, v96, v96
	v_fmac_f32_e32 v104, v98, v98
	v_add_f32_e32 v101, v101, v102
	v_add_f32_e32 v102, v103, v104
	v_add_f32_e32 v101, v101, v102
	v_add_f32_e32 v100, v100, v101
	ds_bpermute_b32 v101, v119, v100
	v_lshl_add_u64 v[82:83], s[30:31], 0, v[116:117]
	v_lshl_add_u64 v[82:83], v[82:83], 0, v[158:159]
	v_lshl_add_u64 v[82:83], v[82:83], 0, v[156:157]
	v_lshl_add_u64 v[82:83], v[82:83], 0, v[154:155]
	v_lshl_add_u64 v[82:83], v[82:83], 0, v[150:151]
	s_waitcnt vmcnt(3)
	v_pk_mul_f32 v[66:67], v[86:87], v[66:67]
	v_pk_mul_f32 v[64:65], v[84:85], v[64:65]
	s_waitcnt vmcnt(2)
	v_pk_mul_f32 v[70:71], v[90:91], v[70:71]
	v_pk_mul_f32 v[68:69], v[88:89], v[68:69]
	s_waitcnt vmcnt(1)
	v_pk_mul_f32 v[74:75], v[94:95], v[74:75]
	v_pk_mul_f32 v[72:73], v[92:93], v[72:73]
	s_waitcnt vmcnt(0)
	v_pk_mul_f32 v[78:79], v[98:99], v[78:79]
	v_pk_mul_f32 v[76:77], v[96:97], v[76:77]
	v_cvt_pk_bf16_f32 v64, v64, v65
	v_cvt_pk_bf16_f32 v65, v66, v67
	v_cvt_pk_bf16_f32 v66, v68, v69
	v_cvt_pk_bf16_f32 v67, v70, v71
	v_cvt_pk_bf16_f32 v68, v72, v73
	v_cvt_pk_bf16_f32 v69, v74, v75
	v_cvt_pk_bf16_f32 v70, v76, v77
	v_cvt_pk_bf16_f32 v71, v78, v79
	ds_write_b128 v173, v[64:67]
	ds_write_b128 v173, v[68:71] offset:64
	s_waitcnt lgkmcnt(0)
	ds_read_b128 v[66:69], v171
	ds_read_b128 v[70:73], v171 offset:1152
	s_waitcnt lgkmcnt(4)
	v_add_f32_e32 v64, v100, v101
	v_add_co_u32_e32 v74, vcc, s62, v82
	ds_bpermute_b32 v65, v118, v64
	s_nop 0
	v_addc_co_u32_e32 v75, vcc, 0, v83, vcc
	s_waitcnt lgkmcnt(2)
	global_store_dwordx4 v[82:83], v[66:69], off
	s_waitcnt lgkmcnt(1)
	global_store_dwordx4 v[74:75], v[70:73], off
	s_waitcnt lgkmcnt(0)
	s_and_saveexec_b64 s[48:49], s[2:3]
	s_cbranch_execz .LBB0_757
	v_lshl_add_u64 v[66:67], v[80:81], 2, s[36:37]
	s_waitcnt lgkmcnt(0)
	v_add_f32_e32 v64, v64, v65
	global_atomic_add_f32 v[66:67], v64, off
.LBB0_757:
	s_or_b64 exec, exec, s[48:49]
	s_addk_i32 s50, 0x80
	s_waitcnt lgkmcnt(0)
	v_or_b32_e32 v64, s50, v162
	v_cmp_lt_i32_e32 vcc, s75, v64
	s_and_saveexec_b64 s[48:49], vcc
	s_xor_b64 s[48:49], exec, s[48:49]
	v_add_u32_e32 v66, 0xffff0000, v64
	v_mov_b32_e32 v67, v137
	v_lshlrev_b64 v[68:69], 12, v[66:67]
	v_lshrrev_b32_e32 v65, 5, v66
	v_lshl_add_u64 v[68:69], s[10:11], 0, v[68:69]
	v_add_u32_e32 v66, 32, v65
	v_mov_b32_e32 v65, v137
	s_or_saveexec_b64 s[48:49], s[48:49]
	s_ashr_i32 s50, s50, 11
	s_xor_b64 exec, exec, s[48:49]
	v_ashrrev_i32_e32 v65, 31, v64
	v_lshlrev_b64 v[66:67], 12, v[64:65]
	v_lshl_add_u64 v[68:69], s[8:9], 0, v[66:67]
	v_mov_b32_e32 v66, s50
	s_or_b64 exec, exec, s[48:49]
	v_lshl_add_u64 v[68:69], v[138:139], 2, v[68:69]
	v_lshl_add_u64 v[68:69], v[140:141], 2, v[68:69]
	v_lshl_add_u64 v[68:69], v[68:69], 0, v[136:137]
	v_lshl_add_u64 v[76:77], v[68:69], 0, v[152:153]
	v_add_co_u32_e32 v80, vcc, 0x8000, v76
	v_mov_b64_e32 v[84:85], s[28:29]
	s_nop 0
	v_addc_co_u32_e32 v81, vcc, 0, v77, vcc
	global_load_dwordx4 v[68:71], v[76:77], off nt
	global_load_dwordx4 v[72:75], v[80:81], off nt
	v_mad_i64_i32 v[84:85], s[48:49], v66, s76, v[84:85]
	v_lshl_add_u64 v[96:97], v[84:85], 0, v[152:153]
	global_load_dwordx4 v[218:221], v[76:77], off offset:128 nt
	global_load_dwordx4 v[222:225], v[80:81], off offset:128 nt
	global_load_dwordx4 v[228:231], v[96:97], off
	global_load_dwordx4 v[232:235], v[96:97], off offset:16
	global_load_dwordx4 v[236:239], v[96:97], off offset:128
	global_load_dwordx4 v[240:243], v[96:97], off offset:144
	v_lshlrev_b64 v[100:101], 11, v[64:65]
	v_lshl_add_u64 v[102:103], s[38:39], 0, v[100:101]
	v_lshl_add_u64 v[102:103], v[102:103], 0, v[158:159]
	v_lshl_add_u64 v[102:103], v[102:103], 0, v[156:157]
	v_mov_b32_e32 v151, v137
	v_lshl_add_u64 v[102:103], v[102:103], 0, v[154:155]
	v_ashrrev_i32_e32 v67, 31, v66
	v_lshl_add_u64 v[102:103], v[102:103], 0, v[150:151]
	v_lshlrev_b64 v[66:67], 12, v[66:67]
	v_lshl_add_u64 v[66:67], s[34:35], 0, v[66:67]
	v_lshl_add_u64 v[66:67], v[66:67], 0, v[152:153]
	s_waitcnt vmcnt(7)
	ds_write_b128 v171, v[68:71]
	s_waitcnt vmcnt(6)
	ds_write_b128 v171, v[72:75] offset:1152
	s_waitcnt lgkmcnt(0)
	ds_read_b128 v[68:71], v172
	ds_read_b128 v[72:75], v172 offset:16
	s_waitcnt lgkmcnt(0)
	s_nop 0
	s_nop 0
	s_waitcnt vmcnt(5)
	ds_write_b128 v171, v[218:221]
	s_waitcnt vmcnt(4)
	ds_write_b128 v171, v[222:225] offset:1152
	s_waitcnt lgkmcnt(0)
	ds_read_b128 v[76:79], v172
	ds_read_b128 v[80:83], v172 offset:16
	s_waitcnt lgkmcnt(0)
	s_nop 0
	s_waitcnt vmcnt(3) lgkmcnt(5)
	v_pk_fma_f32 v[70:71], v[62:63], v[230:231], v[70:71]
	v_pk_fma_f32 v[68:69], v[60:61], v[228:229], v[68:69]
	s_waitcnt vmcnt(2) lgkmcnt(4)
	v_pk_fma_f32 v[74:75], v[58:59], v[234:235], v[74:75]
	v_pk_fma_f32 v[72:73], v[56:57], v[232:233], v[72:73]
	v_cvt_pk_bf16_f32 v56, v68, v69
	v_cvt_pk_bf16_f32 v57, v70, v71
	v_cvt_pk_bf16_f32 v58, v72, v73
	v_cvt_pk_bf16_f32 v59, v74, v75
	ds_write_b128 v173, v[56:59]
	v_add_co_u32_e32 v56, vcc, s62, v102
	v_mul_f32_e32 v84, v69, v69
	s_nop 0
	v_addc_co_u32_e32 v57, vcc, 0, v103, vcc
	v_mul_f32_e32 v85, v71, v71
	v_mul_f32_e32 v86, v73, v73
	v_mul_f32_e32 v87, v75, v75
	v_fmac_f32_e32 v84, v68, v68
	v_fmac_f32_e32 v85, v70, v70
	v_fmac_f32_e32 v86, v72, v72
	v_fmac_f32_e32 v87, v74, v74
	v_add_f32_e32 v84, v84, v85
	v_add_f32_e32 v85, v86, v87
	v_add_f32_e32 v84, v84, v85
	s_waitcnt vmcnt(1) lgkmcnt(2)
	v_pk_fma_f32 v[78:79], v[54:55], v[238:239], v[78:79]
	v_pk_fma_f32 v[76:77], v[52:53], v[236:237], v[76:77]
	s_waitcnt vmcnt(0) lgkmcnt(1)
	v_pk_fma_f32 v[82:83], v[50:51], v[242:243], v[82:83]
	v_pk_fma_f32 v[80:81], v[48:49], v[240:241], v[80:81]
	v_cvt_pk_bf16_f32 v48, v76, v77
	v_cvt_pk_bf16_f32 v49, v78, v79
	v_cvt_pk_bf16_f32 v50, v80, v81
	v_cvt_pk_bf16_f32 v51, v82, v83
	ds_write_b128 v173, v[48:51] offset:64
	s_waitcnt lgkmcnt(0)
	ds_read_b128 v[48:51], v171
	ds_read_b128 v[52:55], v171 offset:1152
	s_waitcnt lgkmcnt(1)
	global_store_dwordx4 v[102:103], v[48:51], off
	s_waitcnt lgkmcnt(0)
	global_store_dwordx4 v[56:57], v[52:55], off
	s_waitcnt lgkmcnt(0)
	global_load_dwordx4 v[48:51], v[66:67], off
	global_load_dwordx4 v[52:55], v[66:67], off offset:16
	global_load_dwordx4 v[56:59], v[66:67], off offset:128
	global_load_dwordx4 v[60:63], v[66:67], off offset:144
	v_mul_f32_e32 v85, v77, v77
	v_mul_f32_e32 v86, v79, v79
	v_mul_f32_e32 v87, v81, v81
	v_mul_f32_e32 v88, v83, v83
	v_fmac_f32_e32 v85, v76, v76
	v_fmac_f32_e32 v86, v78, v78
	v_fmac_f32_e32 v87, v80, v80
	v_fmac_f32_e32 v88, v82, v82
	v_add_f32_e32 v85, v85, v86
	v_add_f32_e32 v86, v87, v88
	v_add_f32_e32 v85, v85, v86
	v_add_f32_e32 v84, v84, v85
	ds_bpermute_b32 v85, v119, v84
	v_lshl_add_u64 v[66:67], s[30:31], 0, v[100:101]
	v_lshl_add_u64 v[66:67], v[66:67], 0, v[158:159]
	v_lshl_add_u64 v[66:67], v[66:67], 0, v[156:157]
	v_lshl_add_u64 v[66:67], v[66:67], 0, v[154:155]
	v_lshl_add_u64 v[66:67], v[66:67], 0, v[150:151]
	s_waitcnt vmcnt(3)
	v_pk_mul_f32 v[50:51], v[70:71], v[50:51]
	v_pk_mul_f32 v[48:49], v[68:69], v[48:49]
	s_waitcnt vmcnt(2)
	v_pk_mul_f32 v[54:55], v[74:75], v[54:55]
	v_pk_mul_f32 v[52:53], v[72:73], v[52:53]
	s_waitcnt vmcnt(1)
	v_pk_mul_f32 v[58:59], v[78:79], v[58:59]
	v_pk_mul_f32 v[56:57], v[76:77], v[56:57]
	s_waitcnt vmcnt(0)
	v_pk_mul_f32 v[62:63], v[82:83], v[62:63]
	v_pk_mul_f32 v[60:61], v[80:81], v[60:61]
	v_cvt_pk_bf16_f32 v48, v48, v49
	v_cvt_pk_bf16_f32 v49, v50, v51
	v_cvt_pk_bf16_f32 v50, v52, v53
	v_cvt_pk_bf16_f32 v51, v54, v55
	v_cvt_pk_bf16_f32 v52, v56, v57
	v_cvt_pk_bf16_f32 v53, v58, v59
	v_cvt_pk_bf16_f32 v54, v60, v61
	v_cvt_pk_bf16_f32 v55, v62, v63
	ds_write_b128 v173, v[48:51]
	ds_write_b128 v173, v[52:55] offset:64
	s_waitcnt lgkmcnt(0)
	ds_read_b128 v[50:53], v171
	ds_read_b128 v[54:57], v171 offset:1152
	s_waitcnt lgkmcnt(4)
	v_add_f32_e32 v48, v84, v85
	v_add_co_u32_e32 v58, vcc, s62, v66
	ds_bpermute_b32 v49, v118, v48
	s_nop 0
	v_addc_co_u32_e32 v59, vcc, 0, v67, vcc
	s_waitcnt lgkmcnt(2)
	global_store_dwordx4 v[66:67], v[50:53], off
	s_waitcnt lgkmcnt(1)
	global_store_dwordx4 v[58:59], v[54:57], off
	s_waitcnt lgkmcnt(0)
	s_and_saveexec_b64 s[48:49], s[2:3]
	s_cbranch_execz .LBB0_763
	v_lshl_add_u64 v[50:51], v[64:65], 2, s[36:37]
	s_waitcnt lgkmcnt(0)
	v_add_f32_e32 v48, v48, v49
	global_atomic_add_f32 v[50:51], v48, off
.LBB0_763:
	s_or_b64 exec, exec, s[48:49]
	s_waitcnt lgkmcnt(0)
	v_or_b32_e32 v48, 16, v64
	v_cmp_lt_i32_e32 vcc, s75, v48
	s_and_saveexec_b64 s[48:49], vcc
	s_xor_b64 s[48:49], exec, s[48:49]
	v_add_u32_e32 v50, 0xffff0010, v64
	v_mov_b32_e32 v51, v137
	v_lshlrev_b64 v[52:53], 12, v[50:51]
	v_lshrrev_b32_e32 v49, 5, v50
	v_lshl_add_u64 v[52:53], s[10:11], 0, v[52:53]
	v_add_u32_e32 v50, 32, v49
	v_mov_b32_e32 v49, v137
	s_andn2_saveexec_b64 s[48:49], s[48:49]
	v_ashrrev_i32_e32 v49, 31, v48
	v_lshlrev_b64 v[50:51], 12, v[48:49]
	v_lshl_add_u64 v[52:53], s[8:9], 0, v[50:51]
	v_mov_b32_e32 v50, s50
	s_or_b64 exec, exec, s[48:49]
	v_lshl_add_u64 v[52:53], v[138:139], 2, v[52:53]
	v_lshl_add_u64 v[52:53], v[140:141], 2, v[52:53]
	v_lshl_add_u64 v[52:53], v[52:53], 0, v[136:137]
	v_lshl_add_u64 v[60:61], v[52:53], 0, v[152:153]
	v_add_co_u32_e32 v66, vcc, 0x8000, v60
	v_mov_b64_e32 v[70:71], s[28:29]
	s_nop 0
	v_addc_co_u32_e32 v67, vcc, 0, v61, vcc
	global_load_dwordx4 v[52:55], v[60:61], off nt
	global_load_dwordx4 v[56:59], v[66:67], off nt
	v_mad_i64_i32 v[70:71], s[48:49], v50, s76, v[70:71]
	v_lshl_add_u64 v[82:83], v[70:71], 0, v[152:153]
	global_load_dwordx4 v[218:221], v[60:61], off offset:128 nt
	global_load_dwordx4 v[222:225], v[66:67], off offset:128 nt
	global_load_dwordx4 v[228:231], v[82:83], off
	global_load_dwordx4 v[232:235], v[82:83], off offset:16
	global_load_dwordx4 v[236:239], v[82:83], off offset:128
	global_load_dwordx4 v[240:243], v[82:83], off offset:144
	v_lshlrev_b64 v[86:87], 11, v[48:49]
	v_lshl_add_u64 v[88:89], s[38:39], 0, v[86:87]
	v_lshl_add_u64 v[88:89], v[88:89], 0, v[158:159]
	v_lshl_add_u64 v[88:89], v[88:89], 0, v[156:157]
	v_mov_b32_e32 v151, v137
	v_lshl_add_u64 v[88:89], v[88:89], 0, v[154:155]
	v_ashrrev_i32_e32 v51, 31, v50
	v_lshl_add_u64 v[88:89], v[88:89], 0, v[150:151]
	v_lshlrev_b64 v[50:51], 12, v[50:51]
	v_lshl_add_u64 v[50:51], s[34:35], 0, v[50:51]
	v_lshl_add_u64 v[50:51], v[50:51], 0, v[152:153]
	s_waitcnt vmcnt(7)
	ds_write_b128 v171, v[52:55]
	s_waitcnt vmcnt(6)
	ds_write_b128 v171, v[56:59] offset:1152
	s_waitcnt lgkmcnt(0)
	ds_read_b128 v[52:55], v172
	ds_read_b128 v[56:59], v172 offset:16
	s_waitcnt lgkmcnt(0)
	s_nop 0
	s_nop 0
	s_waitcnt vmcnt(5)
	ds_write_b128 v171, v[218:221]
	s_waitcnt vmcnt(4)
	ds_write_b128 v171, v[222:225] offset:1152
	s_waitcnt lgkmcnt(0)
	ds_read_b128 v[60:63], v172
	ds_read_b128 v[66:69], v172 offset:16
	s_waitcnt lgkmcnt(0)
	s_nop 0
	s_waitcnt vmcnt(3) lgkmcnt(5)
	v_pk_fma_f32 v[54:55], v[46:47], v[230:231], v[54:55]
	v_pk_fma_f32 v[52:53], v[44:45], v[228:229], v[52:53]
	s_waitcnt vmcnt(2) lgkmcnt(4)
	v_pk_fma_f32 v[58:59], v[42:43], v[234:235], v[58:59]
	v_pk_fma_f32 v[56:57], v[40:41], v[232:233], v[56:57]
	v_cvt_pk_bf16_f32 v40, v52, v53
	v_cvt_pk_bf16_f32 v41, v54, v55
	v_cvt_pk_bf16_f32 v42, v56, v57
	v_cvt_pk_bf16_f32 v43, v58, v59
	ds_write_b128 v173, v[40:43]
	v_add_co_u32_e32 v40, vcc, s62, v88
	v_mul_f32_e32 v65, v53, v53
	s_nop 0
	v_addc_co_u32_e32 v41, vcc, 0, v89, vcc
	v_mul_f32_e32 v70, v55, v55
	v_mul_f32_e32 v71, v57, v57
	v_mul_f32_e32 v72, v59, v59
	v_fmac_f32_e32 v65, v52, v52
	v_fmac_f32_e32 v70, v54, v54
	v_fmac_f32_e32 v71, v56, v56
	v_fmac_f32_e32 v72, v58, v58
	v_add_f32_e32 v65, v65, v70
	v_add_f32_e32 v70, v71, v72
	v_add_f32_e32 v65, v65, v70
	s_waitcnt vmcnt(1) lgkmcnt(2)
	v_pk_fma_f32 v[62:63], v[38:39], v[238:239], v[62:63]
	v_pk_fma_f32 v[60:61], v[36:37], v[236:237], v[60:61]
	s_waitcnt vmcnt(0) lgkmcnt(1)
	v_pk_fma_f32 v[68:69], v[34:35], v[242:243], v[68:69]
	v_pk_fma_f32 v[66:67], v[32:33], v[240:241], v[66:67]
	v_cvt_pk_bf16_f32 v32, v60, v61
	v_cvt_pk_bf16_f32 v33, v62, v63
	v_cvt_pk_bf16_f32 v34, v66, v67
	v_cvt_pk_bf16_f32 v35, v68, v69
	ds_write_b128 v173, v[32:35] offset:64
	s_waitcnt lgkmcnt(0)
	ds_read_b128 v[32:35], v171
	ds_read_b128 v[36:39], v171 offset:1152
	s_waitcnt lgkmcnt(1)
	global_store_dwordx4 v[88:89], v[32:35], off
	s_waitcnt lgkmcnt(0)
	global_store_dwordx4 v[40:41], v[36:39], off
	s_waitcnt lgkmcnt(0)
	global_load_dwordx4 v[32:35], v[50:51], off
	global_load_dwordx4 v[36:39], v[50:51], off offset:16
	global_load_dwordx4 v[40:43], v[50:51], off offset:128
	global_load_dwordx4 v[44:47], v[50:51], off offset:144
	v_mul_f32_e32 v70, v61, v61
	v_mul_f32_e32 v71, v63, v63
	v_mul_f32_e32 v72, v67, v67
	v_mul_f32_e32 v73, v69, v69
	v_fmac_f32_e32 v70, v60, v60
	v_fmac_f32_e32 v71, v62, v62
	v_fmac_f32_e32 v72, v66, v66
	v_fmac_f32_e32 v73, v68, v68
	v_add_f32_e32 v70, v70, v71
	v_add_f32_e32 v71, v72, v73
	v_add_f32_e32 v70, v70, v71
	v_add_f32_e32 v65, v65, v70
	ds_bpermute_b32 v70, v119, v65
	v_lshl_add_u64 v[50:51], s[30:31], 0, v[86:87]
	v_lshl_add_u64 v[50:51], v[50:51], 0, v[158:159]
	v_lshl_add_u64 v[50:51], v[50:51], 0, v[156:157]
	v_lshl_add_u64 v[50:51], v[50:51], 0, v[154:155]
	v_lshl_add_u64 v[50:51], v[50:51], 0, v[150:151]
	s_waitcnt vmcnt(3)
	v_pk_mul_f32 v[34:35], v[54:55], v[34:35]
	v_pk_mul_f32 v[32:33], v[52:53], v[32:33]
	s_waitcnt vmcnt(2)
	v_pk_mul_f32 v[38:39], v[58:59], v[38:39]
	v_pk_mul_f32 v[36:37], v[56:57], v[36:37]
	s_waitcnt vmcnt(1)
	v_pk_mul_f32 v[42:43], v[62:63], v[42:43]
	v_pk_mul_f32 v[40:41], v[60:61], v[40:41]
	s_waitcnt vmcnt(0)
	v_pk_mul_f32 v[46:47], v[68:69], v[46:47]
	v_pk_mul_f32 v[44:45], v[66:67], v[44:45]
	v_cvt_pk_bf16_f32 v32, v32, v33
	v_cvt_pk_bf16_f32 v33, v34, v35
	v_cvt_pk_bf16_f32 v34, v36, v37
	v_cvt_pk_bf16_f32 v35, v38, v39
	v_cvt_pk_bf16_f32 v36, v40, v41
	v_cvt_pk_bf16_f32 v37, v42, v43
	v_cvt_pk_bf16_f32 v38, v44, v45
	v_cvt_pk_bf16_f32 v39, v46, v47
	ds_write_b128 v173, v[32:35]
	ds_write_b128 v173, v[36:39] offset:64
	s_waitcnt lgkmcnt(0)
	ds_read_b128 v[34:37], v171
	ds_read_b128 v[38:41], v171 offset:1152
	s_waitcnt lgkmcnt(4)
	v_add_f32_e32 v32, v65, v70
	v_add_co_u32_e32 v42, vcc, s62, v50
	ds_bpermute_b32 v33, v118, v32
	s_nop 0
	v_addc_co_u32_e32 v43, vcc, 0, v51, vcc
	s_waitcnt lgkmcnt(2)
	global_store_dwordx4 v[50:51], v[34:37], off
	s_waitcnt lgkmcnt(1)
	global_store_dwordx4 v[42:43], v[38:41], off
	s_waitcnt lgkmcnt(0)
	s_and_saveexec_b64 s[48:49], s[2:3]
	s_cbranch_execz .LBB0_769
	v_lshl_add_u64 v[34:35], v[48:49], 2, s[36:37]
	s_waitcnt lgkmcnt(0)
	v_add_f32_e32 v32, v32, v33
	global_atomic_add_f32 v[34:35], v32, off
.LBB0_769:
	s_or_b64 exec, exec, s[48:49]
	s_waitcnt lgkmcnt(0)
	v_or_b32_e32 v32, 32, v64
	v_cmp_lt_i32_e32 vcc, s75, v32
	s_and_saveexec_b64 s[48:49], vcc
	s_xor_b64 s[48:49], exec, s[48:49]
	v_add_u32_e32 v34, 0xffff0020, v64
	v_mov_b32_e32 v35, v137
	v_lshlrev_b64 v[36:37], 12, v[34:35]
	v_lshrrev_b32_e32 v33, 5, v34
	v_lshl_add_u64 v[36:37], s[10:11], 0, v[36:37]
	v_add_u32_e32 v34, 32, v33
	v_mov_b32_e32 v33, v137
	s_andn2_saveexec_b64 s[48:49], s[48:49]
	v_ashrrev_i32_e32 v33, 31, v32
	v_lshlrev_b64 v[34:35], 12, v[32:33]
	v_lshl_add_u64 v[36:37], s[8:9], 0, v[34:35]
	v_mov_b32_e32 v34, s50
	s_or_b64 exec, exec, s[48:49]
	v_lshl_add_u64 v[36:37], v[138:139], 2, v[36:37]
	v_lshl_add_u64 v[36:37], v[140:141], 2, v[36:37]
	v_lshl_add_u64 v[36:37], v[36:37], 0, v[136:137]
	v_lshl_add_u64 v[44:45], v[36:37], 0, v[152:153]
	v_add_co_u32_e32 v48, vcc, 0x8000, v44
	v_mov_b64_e32 v[52:53], s[28:29]
	s_nop 0
	v_addc_co_u32_e32 v49, vcc, 0, v45, vcc
	global_load_dwordx4 v[36:39], v[44:45], off nt
	global_load_dwordx4 v[40:43], v[48:49], off nt
	v_mad_i64_i32 v[52:53], s[48:49], v34, s76, v[52:53]
	v_lshl_add_u64 v[66:67], v[52:53], 0, v[152:153]
	global_load_dwordx4 v[218:221], v[44:45], off offset:128 nt
	global_load_dwordx4 v[222:225], v[48:49], off offset:128 nt
	global_load_dwordx4 v[228:231], v[66:67], off
	global_load_dwordx4 v[232:235], v[66:67], off offset:16
	global_load_dwordx4 v[236:239], v[66:67], off offset:128
	global_load_dwordx4 v[240:243], v[66:67], off offset:144
	v_lshlrev_b64 v[70:71], 11, v[32:33]
	v_lshl_add_u64 v[72:73], s[38:39], 0, v[70:71]
	v_lshl_add_u64 v[72:73], v[72:73], 0, v[158:159]
	v_lshl_add_u64 v[72:73], v[72:73], 0, v[156:157]
	v_mov_b32_e32 v151, v137
	v_lshl_add_u64 v[72:73], v[72:73], 0, v[154:155]
	v_ashrrev_i32_e32 v35, 31, v34
	v_lshl_add_u64 v[72:73], v[72:73], 0, v[150:151]
	v_lshlrev_b64 v[34:35], 12, v[34:35]
	v_lshl_add_u64 v[34:35], s[34:35], 0, v[34:35]
	v_lshl_add_u64 v[34:35], v[34:35], 0, v[152:153]
	s_waitcnt vmcnt(7)
	ds_write_b128 v171, v[36:39]
	s_waitcnt vmcnt(6)
	ds_write_b128 v171, v[40:43] offset:1152
	s_waitcnt lgkmcnt(0)
	ds_read_b128 v[36:39], v172
	ds_read_b128 v[40:43], v172 offset:16
	s_waitcnt lgkmcnt(0)
	s_nop 0
	s_nop 0
	s_waitcnt vmcnt(5)
	ds_write_b128 v171, v[218:221]
	s_waitcnt vmcnt(4)
	ds_write_b128 v171, v[222:225] offset:1152
	s_waitcnt lgkmcnt(0)
	ds_read_b128 v[44:47], v172
	ds_read_b128 v[48:51], v172 offset:16
	s_waitcnt lgkmcnt(0)
	s_nop 0
	s_waitcnt vmcnt(3) lgkmcnt(5)
	v_pk_fma_f32 v[38:39], v[30:31], v[230:231], v[38:39]
	v_pk_fma_f32 v[36:37], v[28:29], v[228:229], v[36:37]
	s_waitcnt vmcnt(2) lgkmcnt(4)
	v_pk_fma_f32 v[42:43], v[26:27], v[234:235], v[42:43]
	v_pk_fma_f32 v[40:41], v[24:25], v[232:233], v[40:41]
	v_cvt_pk_bf16_f32 v24, v36, v37
	v_cvt_pk_bf16_f32 v25, v38, v39
	v_cvt_pk_bf16_f32 v26, v40, v41
	v_cvt_pk_bf16_f32 v27, v42, v43
	ds_write_b128 v173, v[24:27]
	v_add_co_u32_e32 v24, vcc, s62, v72
	v_mul_f32_e32 v52, v37, v37
	s_nop 0
	v_addc_co_u32_e32 v25, vcc, 0, v73, vcc
	v_mul_f32_e32 v53, v39, v39
	v_mul_f32_e32 v54, v41, v41
	v_mul_f32_e32 v55, v43, v43
	v_fmac_f32_e32 v52, v36, v36
	v_fmac_f32_e32 v53, v38, v38
	v_fmac_f32_e32 v54, v40, v40
	v_fmac_f32_e32 v55, v42, v42
	v_add_f32_e32 v52, v52, v53
	v_add_f32_e32 v53, v54, v55
	v_add_f32_e32 v52, v52, v53
	s_waitcnt vmcnt(1) lgkmcnt(2)
	v_pk_fma_f32 v[46:47], v[22:23], v[238:239], v[46:47]
	v_pk_fma_f32 v[44:45], v[20:21], v[236:237], v[44:45]
	s_waitcnt vmcnt(0) lgkmcnt(1)
	v_pk_fma_f32 v[50:51], v[18:19], v[242:243], v[50:51]
	v_pk_fma_f32 v[48:49], v[16:17], v[240:241], v[48:49]
	v_cvt_pk_bf16_f32 v16, v44, v45
	v_cvt_pk_bf16_f32 v17, v46, v47
	v_cvt_pk_bf16_f32 v18, v48, v49
	v_cvt_pk_bf16_f32 v19, v50, v51
	ds_write_b128 v173, v[16:19] offset:64
	s_waitcnt lgkmcnt(0)
	ds_read_b128 v[16:19], v171
	ds_read_b128 v[20:23], v171 offset:1152
	s_waitcnt lgkmcnt(1)
	global_store_dwordx4 v[72:73], v[16:19], off
	s_waitcnt lgkmcnt(0)
	global_store_dwordx4 v[24:25], v[20:23], off
	s_waitcnt lgkmcnt(0)
	global_load_dwordx4 v[16:19], v[34:35], off
	global_load_dwordx4 v[20:23], v[34:35], off offset:16
	global_load_dwordx4 v[24:27], v[34:35], off offset:128
	global_load_dwordx4 v[28:31], v[34:35], off offset:144
	v_mul_f32_e32 v53, v45, v45
	v_mul_f32_e32 v54, v47, v47
	v_mul_f32_e32 v55, v49, v49
	v_mul_f32_e32 v56, v51, v51
	v_fmac_f32_e32 v53, v44, v44
	v_fmac_f32_e32 v54, v46, v46
	v_fmac_f32_e32 v55, v48, v48
	v_fmac_f32_e32 v56, v50, v50
	v_add_f32_e32 v53, v53, v54
	v_add_f32_e32 v54, v55, v56
	v_add_f32_e32 v53, v53, v54
	v_add_f32_e32 v52, v52, v53
	ds_bpermute_b32 v53, v119, v52
	v_lshl_add_u64 v[34:35], s[30:31], 0, v[70:71]
	v_lshl_add_u64 v[34:35], v[34:35], 0, v[158:159]
	v_lshl_add_u64 v[34:35], v[34:35], 0, v[156:157]
	v_lshl_add_u64 v[34:35], v[34:35], 0, v[154:155]
	v_lshl_add_u64 v[34:35], v[34:35], 0, v[150:151]
	s_waitcnt vmcnt(3)
	v_pk_mul_f32 v[18:19], v[38:39], v[18:19]
	v_pk_mul_f32 v[16:17], v[36:37], v[16:17]
	s_waitcnt vmcnt(2)
	v_pk_mul_f32 v[22:23], v[42:43], v[22:23]
	v_pk_mul_f32 v[20:21], v[40:41], v[20:21]
	s_waitcnt vmcnt(1)
	v_pk_mul_f32 v[26:27], v[46:47], v[26:27]
	v_pk_mul_f32 v[24:25], v[44:45], v[24:25]
	s_waitcnt vmcnt(0)
	v_pk_mul_f32 v[30:31], v[50:51], v[30:31]
	v_pk_mul_f32 v[28:29], v[48:49], v[28:29]
	v_cvt_pk_bf16_f32 v16, v16, v17
	v_cvt_pk_bf16_f32 v17, v18, v19
	v_cvt_pk_bf16_f32 v18, v20, v21
	v_cvt_pk_bf16_f32 v19, v22, v23
	v_cvt_pk_bf16_f32 v20, v24, v25
	v_cvt_pk_bf16_f32 v21, v26, v27
	v_cvt_pk_bf16_f32 v22, v28, v29
	v_cvt_pk_bf16_f32 v23, v30, v31
	ds_write_b128 v173, v[16:19]
	ds_write_b128 v173, v[20:23] offset:64
	s_waitcnt lgkmcnt(0)
	ds_read_b128 v[18:21], v171
	ds_read_b128 v[22:25], v171 offset:1152
	s_waitcnt lgkmcnt(4)
	v_add_f32_e32 v16, v52, v53
	v_add_co_u32_e32 v26, vcc, s62, v34
	ds_bpermute_b32 v17, v118, v16
	s_nop 0
	v_addc_co_u32_e32 v27, vcc, 0, v35, vcc
	s_waitcnt lgkmcnt(2)
	global_store_dwordx4 v[34:35], v[18:21], off
	s_waitcnt lgkmcnt(1)
	global_store_dwordx4 v[26:27], v[22:25], off
	s_waitcnt lgkmcnt(0)
	s_and_saveexec_b64 s[48:49], s[2:3]
	s_cbranch_execz .LBB0_775
	v_lshl_add_u64 v[18:19], v[32:33], 2, s[36:37]
	s_waitcnt lgkmcnt(0)
	v_add_f32_e32 v16, v16, v17
	global_atomic_add_f32 v[18:19], v16, off
.LBB0_775:
	s_or_b64 exec, exec, s[48:49]
	s_waitcnt lgkmcnt(0)
	v_or_b32_e32 v16, 48, v64
	v_cmp_lt_i32_e32 vcc, s75, v16
	s_and_saveexec_b64 s[48:49], vcc
	s_xor_b64 s[48:49], exec, s[48:49]
	v_add_u32_e32 v18, 0xffff0030, v64
	v_mov_b32_e32 v19, v137
	v_lshlrev_b64 v[20:21], 12, v[18:19]
	v_lshrrev_b32_e32 v17, 5, v18
	v_lshl_add_u64 v[20:21], s[10:11], 0, v[20:21]
	v_add_u32_e32 v18, 32, v17
	v_mov_b32_e32 v17, v137
	s_andn2_saveexec_b64 s[48:49], s[48:49]
	v_ashrrev_i32_e32 v17, 31, v16
	v_lshlrev_b64 v[18:19], 12, v[16:17]
	v_lshl_add_u64 v[20:21], s[8:9], 0, v[18:19]
	v_mov_b32_e32 v18, s50
	s_or_b64 exec, exec, s[48:49]
	v_lshl_add_u64 v[20:21], v[138:139], 2, v[20:21]
	v_lshl_add_u64 v[20:21], v[140:141], 2, v[20:21]
	v_lshl_add_u64 v[20:21], v[20:21], 0, v[136:137]
	v_lshl_add_u64 v[28:29], v[20:21], 0, v[152:153]
	v_add_co_u32_e32 v32, vcc, 0x8000, v28
	v_mov_b64_e32 v[36:37], s[28:29]
	s_nop 0
	v_addc_co_u32_e32 v33, vcc, 0, v29, vcc
	global_load_dwordx4 v[20:23], v[28:29], off nt
	global_load_dwordx4 v[24:27], v[32:33], off nt
	v_mad_i64_i32 v[36:37], s[48:49], v18, s76, v[36:37]
	v_lshl_add_u64 v[48:49], v[36:37], 0, v[152:153]
	global_load_dwordx4 v[218:221], v[28:29], off offset:128 nt
	global_load_dwordx4 v[222:225], v[32:33], off offset:128 nt
	global_load_dwordx4 v[228:231], v[48:49], off
	global_load_dwordx4 v[232:235], v[48:49], off offset:16
	global_load_dwordx4 v[236:239], v[48:49], off offset:128
	global_load_dwordx4 v[240:243], v[48:49], off offset:144
	v_lshlrev_b64 v[52:53], 11, v[16:17]
	v_lshl_add_u64 v[54:55], s[38:39], 0, v[52:53]
	v_lshl_add_u64 v[54:55], v[54:55], 0, v[158:159]
	v_lshl_add_u64 v[54:55], v[54:55], 0, v[156:157]
	v_mov_b32_e32 v151, v137
	v_lshl_add_u64 v[54:55], v[54:55], 0, v[154:155]
	v_ashrrev_i32_e32 v19, 31, v18
	v_lshl_add_u64 v[54:55], v[54:55], 0, v[150:151]
	v_lshlrev_b64 v[18:19], 12, v[18:19]
	v_lshl_add_u64 v[18:19], s[34:35], 0, v[18:19]
	v_lshl_add_u64 v[18:19], v[18:19], 0, v[152:153]
	s_waitcnt vmcnt(7)
	ds_write_b128 v171, v[20:23]
	s_waitcnt vmcnt(6)
	ds_write_b128 v171, v[24:27] offset:1152
	s_waitcnt lgkmcnt(0)
	ds_read_b128 v[20:23], v172
	ds_read_b128 v[24:27], v172 offset:16
	s_waitcnt lgkmcnt(0)
	s_nop 0
	s_nop 0
	s_waitcnt vmcnt(5)
	ds_write_b128 v171, v[218:221]
	s_waitcnt vmcnt(4)
	ds_write_b128 v171, v[222:225] offset:1152
	s_waitcnt lgkmcnt(0)
	ds_read_b128 v[28:31], v172
	ds_read_b128 v[32:35], v172 offset:16
	s_waitcnt lgkmcnt(0)
	s_nop 0
	s_waitcnt vmcnt(3) lgkmcnt(5)
	v_pk_fma_f32 v[22:23], v[14:15], v[230:231], v[22:23]
	v_pk_fma_f32 v[20:21], v[12:13], v[228:229], v[20:21]
	s_waitcnt vmcnt(2) lgkmcnt(4)
	v_pk_fma_f32 v[26:27], v[10:11], v[234:235], v[26:27]
	v_pk_fma_f32 v[24:25], v[8:9], v[232:233], v[24:25]
	v_cvt_pk_bf16_f32 v8, v20, v21
	v_cvt_pk_bf16_f32 v9, v22, v23
	v_cvt_pk_bf16_f32 v10, v24, v25
	v_cvt_pk_bf16_f32 v11, v26, v27
	ds_write_b128 v173, v[8:11]
	v_add_co_u32_e32 v8, vcc, s62, v54
	v_mul_f32_e32 v36, v21, v21
	s_nop 0
	v_addc_co_u32_e32 v9, vcc, 0, v55, vcc
	v_mul_f32_e32 v37, v23, v23
	v_mul_f32_e32 v38, v25, v25
	v_mul_f32_e32 v39, v27, v27
	v_fmac_f32_e32 v36, v20, v20
	v_fmac_f32_e32 v37, v22, v22
	v_fmac_f32_e32 v38, v24, v24
	v_fmac_f32_e32 v39, v26, v26
	v_add_f32_e32 v36, v36, v37
	v_add_f32_e32 v37, v38, v39
	v_add_f32_e32 v36, v36, v37
	s_waitcnt vmcnt(1) lgkmcnt(2)
	v_pk_fma_f32 v[30:31], v[6:7], v[238:239], v[30:31]
	v_pk_fma_f32 v[28:29], v[4:5], v[236:237], v[28:29]
	s_waitcnt vmcnt(0) lgkmcnt(1)
	v_pk_fma_f32 v[34:35], v[2:3], v[242:243], v[34:35]
	v_pk_fma_f32 v[32:33], v[0:1], v[240:241], v[32:33]
	v_cvt_pk_bf16_f32 v0, v28, v29
	v_cvt_pk_bf16_f32 v1, v30, v31
	v_cvt_pk_bf16_f32 v2, v32, v33
	v_cvt_pk_bf16_f32 v3, v34, v35
	ds_write_b128 v173, v[0:3] offset:64
	s_waitcnt lgkmcnt(0)
	ds_read_b128 v[0:3], v171
	ds_read_b128 v[4:7], v171 offset:1152
	s_waitcnt lgkmcnt(1)
	global_store_dwordx4 v[54:55], v[0:3], off
	s_waitcnt lgkmcnt(0)
	global_store_dwordx4 v[8:9], v[4:7], off
	s_waitcnt lgkmcnt(0)
	global_load_dwordx4 v[0:3], v[18:19], off
	global_load_dwordx4 v[4:7], v[18:19], off offset:16
	global_load_dwordx4 v[8:11], v[18:19], off offset:128
	global_load_dwordx4 v[12:15], v[18:19], off offset:144
	v_mul_f32_e32 v37, v29, v29
	v_mul_f32_e32 v38, v31, v31
	v_mul_f32_e32 v39, v33, v33
	v_mul_f32_e32 v40, v35, v35
	v_fmac_f32_e32 v37, v28, v28
	v_fmac_f32_e32 v38, v30, v30
	v_fmac_f32_e32 v39, v32, v32
	v_fmac_f32_e32 v40, v34, v34
	v_add_f32_e32 v37, v37, v38
	v_add_f32_e32 v38, v39, v40
	v_add_f32_e32 v37, v37, v38
	v_add_f32_e32 v36, v36, v37
	ds_bpermute_b32 v37, v119, v36
	v_lshl_add_u64 v[18:19], s[30:31], 0, v[52:53]
	v_lshl_add_u64 v[18:19], v[18:19], 0, v[158:159]
	v_lshl_add_u64 v[18:19], v[18:19], 0, v[156:157]
	v_lshl_add_u64 v[18:19], v[18:19], 0, v[154:155]
	v_lshl_add_u64 v[18:19], v[18:19], 0, v[150:151]
	s_waitcnt vmcnt(3)
	v_pk_mul_f32 v[2:3], v[22:23], v[2:3]
	v_pk_mul_f32 v[0:1], v[20:21], v[0:1]
	s_waitcnt vmcnt(2)
	v_pk_mul_f32 v[6:7], v[26:27], v[6:7]
	v_pk_mul_f32 v[4:5], v[24:25], v[4:5]
	s_waitcnt vmcnt(1)
	v_pk_mul_f32 v[10:11], v[30:31], v[10:11]
	v_pk_mul_f32 v[8:9], v[28:29], v[8:9]
	s_waitcnt vmcnt(0)
	v_pk_mul_f32 v[14:15], v[34:35], v[14:15]
	v_pk_mul_f32 v[12:13], v[32:33], v[12:13]
	v_cvt_pk_bf16_f32 v0, v0, v1
	v_cvt_pk_bf16_f32 v1, v2, v3
	v_cvt_pk_bf16_f32 v2, v4, v5
	v_cvt_pk_bf16_f32 v3, v6, v7
	v_cvt_pk_bf16_f32 v4, v8, v9
	v_cvt_pk_bf16_f32 v5, v10, v11
	v_cvt_pk_bf16_f32 v6, v12, v13
	v_cvt_pk_bf16_f32 v7, v14, v15
	ds_write_b128 v173, v[0:3]
	ds_write_b128 v173, v[4:7] offset:64
	s_waitcnt lgkmcnt(0)
	ds_read_b128 v[2:5], v171
	ds_read_b128 v[6:9], v171 offset:1152
	s_waitcnt lgkmcnt(4)
	v_add_f32_e32 v0, v36, v37
	v_add_co_u32_e32 v10, vcc, s62, v18
	ds_bpermute_b32 v1, v118, v0
	s_nop 0
	v_addc_co_u32_e32 v11, vcc, 0, v19, vcc
	s_waitcnt lgkmcnt(2)
	global_store_dwordx4 v[18:19], v[2:5], off
	s_waitcnt lgkmcnt(1)
	global_store_dwordx4 v[10:11], v[6:9], off
	s_waitcnt lgkmcnt(0)
	s_and_saveexec_b64 s[48:49], s[2:3]
	s_cbranch_execz .LBB0_781
	v_lshl_add_u64 v[2:3], v[16:17], 2, s[36:37]
	s_waitcnt lgkmcnt(0)
	v_add_f32_e32 v0, v0, v1
	global_atomic_add_f32 v[2:3], v0, off

.LBB0_1309:
	s_cmp_lt_i32 s20, 10
	s_cselect_b64 s[4:5], -1, 0
	s_and_b64 s[6:7], s[4:5], s[2:3]
	s_andn2_b64 vcc, exec, s[6:7]
	s_cbranch_vccnz .LBB0_1458
	s_cmpk_eq_i32 s13, 0x100
	s_cselect_b64 s[26:27], -1, 0
	s_cmpk_lg_i32 s13, 0x100
	s_cselect_b64 s[28:29], -1, 0
	s_ashr_i32 s2, s12, 3
	s_and_b32 s4, s2, -8
	s_mov_b64 s[2:3], s[0:1]
	s_and_b32 s63, s12, 7
	s_load_dwordx2 s[8:9], s[2:3], 0xd8
	s_lshr_b32 s62, s12, 3
	s_or_b32 s64, s4, s63
	s_cmpk_lt_i32 s12, 0x80
	s_cselect_b64 s[18:19], -1, 0
	s_waitcnt lgkmcnt(0)
	s_and_b64 s[30:31], s[18:19], s[26:27]
	s_add_u32 s16, s8, 0x14900000
	s_addc_u32 s17, s9, 0
	s_add_u32 s56, s8, 0x23b00000
	s_addc_u32 s57, s9, 0
	s_add_u32 s58, s8, 0xc200000
	s_addc_u32 s59, s9, 0
	s_add_u32 s60, s8, 0x2dc00000
	s_addc_u32 s61, s9, 0
	s_add_u32 s10, s8, 0xc800000
	s_addc_u32 s11, s9, 0
	s_add_u32 s14, s8, 0x1800000
	s_addc_u32 s15, s9, 0
	s_mov_b32 s35, 0
	s_movk_i32 s65, 0xff
	s_movk_i32 s67, 0xc00
	v_mov_b32_e32 v145, 0
	s_mov_b64 s[36:37], 0x1000
	s_movk_i32 s68, 0x90
	s_movk_i32 s69, 0x50
	s_mov_b32 s70, 0x5040100
	s_mov_b32 s71, 0x7060302
	s_mov_b32 s72, 0x41000000
	s_mov_b64 s[38:39], 0x20000
	s_waitcnt vmcnt(0)
	v_mbcnt_hi_u32_b32 v179, -1, v185
	v_and_b32_e32 v210, 0xff, v181
	v_lshrrev_b32_e32 v240, 3, v210
	v_and_b32_e32 v241, 7, v210
	v_lshlrev_b32_e32 v211, 11, v240
	v_lshl_or_b32 v211, v241, 4, v211
	v_add_u32_e32 v218, 0x10000, v211
	v_mul_u32_u24_e32 v214, 0x90, v240
	v_lshl_add_u32 v214, v241, 4, v214
	v_and_b32_e32 v240, 3, v210
	v_bfe_u32 v241, v210, 6, 2
	v_lshl_or_b32 v240, v241, 2, v240
	v_bfe_u32 v241, v210, 2, 4
	v_lshlrev_b32_e32 v212, 13, v240
	v_lshl_or_b32 v212, v241, 3, v212
	v_add_u32_e32 v217, 0x1000, v212
	v_and_b32_e32 v242, 12, v240
	v_and_b32_e32 v243, 1, v240
	v_lshl_or_b32 v242, v243, 1, v242
	v_bfe_u32 v243, v240, 1, 1
	v_or_b32_e32 v242, v242, v243
	v_mul_u32_u24_e32 v215, 0x240, v241
	v_lshl_add_u32 v215, v242, 3, v215
	v_add_u32_e32 v215, 0x2000, v215
	v_lshlrev_b32_e32 v213, 4, v210
	v_lshrrev_b32_e32 v240, 2, v210
	v_mul_u32_u24_e32 v216, 0x50, v240
	v_and_b32_e32 v240, 3, v210
	v_lshl_add_u32 v216, v240, 4, v216
	v_add_u32_e32 v216, 0x4800, v216
	v_lshrrev_b32_e32 v240, 8, v181
	v_mul_u32_u24_e32 v240, 0x5c00, v240
	v_add_u32_e32 v214, v214, v240
	v_add_u32_e32 v215, v215, v240
	v_add_u32_e32 v216, v216, v240
	s_mov_b32 s74, 0
	s_barrier
	s_branch .LBB0_1314

.LBB0_1324:
	s_cmp_lt_u32 s74, 8
	s_cselect_b64 s[2:3], -1, 0
	s_and_b64 s[2:3], s[30:31], s[2:3]
	s_cmp_eq_u32 s73, 3
	s_cselect_b64 s[4:5], -1, 0
	s_and_b64 s[2:3], s[2:3], s[4:5]
	s_and_b64 vcc, exec, s[2:3]
	s_cbranch_vccnz .LBB0_1312
	v_mov_b32_e32 v163, v181
	s_lshl_b32 s2, s75, 7
	v_ashrrev_i32_e32 v21, 6, v163
	s_and_b32 s48, s2, 0xfffff800
	v_readfirstlane_b32 s41, v21
	s_lshl_b32 s2, s73, 8
	s_ashr_i32 s77, s41, 1
	s_lshl_b32 s3, s41, 5
	s_add_i32 s4, s48, s2
	s_lshl_b32 s2, s77, 6
	s_and_b32 s3, s3, 32
	s_lshl_b32 s76, s73, 2
	s_and_b32 s79, s75, 15
	s_or_b32 s5, s2, s3
	s_cmpk_lt_i32 s5, 0x100
	s_cselect_b64 s[42:43], -1, 0
	s_cmpk_gt_i32 s5, 0xff
	s_cselect_b64 s[44:45], -1, 0
	s_and_b64 s[2:3], s[44:45], exec
	s_cselect_b32 s2, 0, s5
	v_and_b32_e32 v162, 31, v163
	s_add_i32 s40, s4, s2
	v_or_b32_e32 v3, s40, v162
	v_mov_b64_e32 v[0:1], s[16:17]
	s_ashr_i32 s49, s48, 31
	v_mad_i64_i32 v[0:1], s[2:3], v3, s67, v[0:1]
	s_lshl_b64 s[4:5], s[48:49], 11
	s_add_u32 s2, s56, s4
	s_addc_u32 s3, s57, s5
	s_lshl_b32 s78, s79, 7
	v_bfe_u32 v2, v163, 5, 1
	s_mul_i32 s34, s79, 0xc0
	s_add_u32 s2, s2, s78
	v_lshl_add_u64 v[0:1], v[0:1], 0, s[34:35]
	v_lshlrev_b32_e32 v144, 4, v2
	s_addc_u32 s3, s3, 0
	s_lshl_b64 s[82:83], s[48:49], 11
	s_add_u32 s82, s82, s78
	s_addc_u32 s83, s83, 0
	s_add_u32 s84, s82, 0x2dc00000
	s_addc_u32 s85, s83, 0
	s_add_u32 s82, s82, 0x23b00000
	s_addc_u32 s83, s83, 0
	s_add_u32 s82, s82, s8
	s_addc_u32 s83, s83, s9
	s_add_u32 s84, s84, s8
	s_addc_u32 s85, s85, s9
	s_lshl_b64 s[86:87], s[48:49], 6
	s_add_u32 s86, s86, 0xc200000
	s_addc_u32 s87, s87, 0
	s_add_u32 s86, s86, s8
	s_addc_u32 s87, s87, s9
	s_lshr_b32 s88, s41, 2
	s_lshl_b32 s89, s88, 17
	s_add_u32 s82, s82, s89
	s_addc_u32 s83, s83, 0
	s_add_u32 s84, s84, s89
	s_addc_u32 s85, s85, 0
	s_lshl_b32 s89, s88, 12
	s_add_u32 s86, s86, s89
	s_addc_u32 s87, s87, 0
	s_or_b32 s34, s76, 3
	v_lshl_add_u64 v[0:1], v[0:1], 0, v[144:145]
	s_min_i32 s52, s34, 0
	global_load_dwordx4 v[100:103], v[0:1], off
	global_load_dwordx4 v[96:99], v[0:1], off offset:32
	global_load_dwordx4 v[92:95], v[0:1], off offset:64
	global_load_dwordx4 v[88:91], v[0:1], off offset:96
	global_load_dwordx4 v[84:87], v[0:1], off offset:128
	global_load_dwordx4 v[80:83], v[0:1], off offset:160
	s_ashr_i32 s53, s52, 31
	s_lshl_b64 s[46:47], s[48:49], 6
	v_and_b32_e32 v161, 7, v163
	s_lshl_b64 s[50:51], s[52:53], 17
	v_ashrrev_i32_e32 v17, 3, v163
	v_lshlrev_b32_e32 v166, 4, v161
	s_add_u32 s2, s2, s50
	v_lshl_or_b32 v16, v17, 11, v166
	v_mov_b32_e32 v0, v145
	v_mov_b32_e32 v1, v145
	v_mov_b32_e32 v2, v145
	v_mov_b32_e32 v3, v145
	v_mov_b32_e32 v4, v145
	v_mov_b32_e32 v5, v145
	v_mov_b32_e32 v6, v145
	v_mov_b32_e32 v7, v145
	v_mov_b32_e32 v8, v145
	v_mov_b32_e32 v9, v145
	v_mov_b32_e32 v10, v145
	v_mov_b32_e32 v11, v145
	v_mov_b32_e32 v12, v145
	v_mov_b32_e32 v13, v145
	v_mov_b32_e32 v14, v145
	v_mov_b32_e32 v15, v145
	s_addc_u32 s3, s3, s51
	v_add_u32_e32 v19, 0xffffff00, v163
	v_ashrrev_i32_e32 v22, 2, v19
	v_and_b32_e32 v18, 3, v163
	v_lshlrev_b32_e32 v19, 6, v22
	v_and_b32_e32 v19, 0xfc0, v19
	v_lshlrev_b32_e32 v20, 4, v18
	v_cmp_lt_i32_e64 s[2:3], s65, v163
	s_and_saveexec_b64 s[54:55], s[2:3]
	s_xor_b64 s[54:55], exec, s[54:55]
	s_cbranch_execz .LBB0_1327
	s_add_u32 s34, s58, s46
	s_addc_u32 s80, s59, s47
	s_lshl_b64 s[52:53], s[52:53], 12
	s_add_u32 s52, s34, s52
	v_or_b32_e32 v23, v19, v20
	s_addc_u32 s53, s80, s53

.LBB0_1329:
	s_or_b64 exec, exec, s[52:53]
	v_mul_lo_u32 v167, v17, s68
	v_add3_u32 v17, 0, v167, v166
	s_waitcnt vmcnt(0)
	v_lshlrev_b32_e32 v17, 4, v163
	v_mul_lo_u32 v168, v22, s69
	v_and_b32_e32 v169, 48, v17
	s_and_saveexec_b64 s[48:49], s[2:3]
	s_xor_b64 s[48:49], exec, s[48:49]
	v_add3_u32 v17, 0, v168, v169
	s_or_saveexec_b64 s[48:49], s[48:49]
	v_bfrev_b32_e32 v17, v163
	v_lshrrev_b32_e32 v17, 30, v17
	v_or_b32_e32 v17, v24, v17
	v_lshlrev_b32_e32 v170, 3, v17
	v_mul_u32_u24_e32 v172, 0x90, v23
	s_xor_b64 exec, exec, s[48:49]
	s_cbranch_execz .LBB0_1333
	v_add3_u32 v17, 0, v170, v172
	v_perm_b32 v22, v148, v146, s70
	v_perm_b32 v23, v152, v150, s70
	v_perm_b32 v24, v148, v146, s71
	v_perm_b32 v25, v152, v150, s71
	v_add_u32_e32 v17, 0x2000, v17
	v_perm_b32 v22, v149, v147, s70
	v_perm_b32 v23, v153, v151, s70
	v_perm_b32 v24, v149, v147, s71
	v_perm_b32 v25, v153, v151, s71
.LBB0_1333:
	s_or_b64 exec, exec, s[48:49]
	global_load_dwordx4 v[220:223], v211, s[82:83]
	global_load_dwordx4 v[224:227], v218, s[82:83]
	global_load_dwordx2 v[228:229], v212, s[84:85]
	global_load_dwordx2 v[230:231], v212, s[84:85] offset:2048
	global_load_dwordx2 v[232:233], v217, s[84:85]
	global_load_dwordx2 v[234:235], v217, s[84:85] offset:2048
	global_load_dwordx4 v[236:239], v213, s[86:87]
	s_add_u32 s82, s82, 0x40000
	s_addc_u32 s83, s83, 0
	s_add_u32 s84, s84, 0x40000
	s_addc_u32 s85, s85, 0
	s_add_u32 s86, s86, 0x2000
	s_addc_u32 s87, s87, 0
	s_cmp_eq_u32 s88, 0
	s_cbranch_scc0 .Lp9m_pro_g1
	s_waitcnt vmcnt(0)
	ds_write_b128 v214, v[220:223]
	ds_write_b128 v214, v[224:227] offset:4608
	v_perm_b32 v240, v230, v228, s70
	v_perm_b32 v241, v234, v232, s70
	v_perm_b32 v242, v230, v228, s71
	v_perm_b32 v243, v234, v232, s71
	ds_write2_b64 v215, v[240:241], v[242:243] offset0:128 offset1:146
	v_perm_b32 v244, v231, v229, s70
	v_perm_b32 v245, v235, v233, s70
	v_perm_b32 v246, v231, v229, s71
	v_perm_b32 v247, v235, v233, s71
	ds_write2_b64 v215, v[244:245], v[246:247] offset0:164 offset1:182
	ds_write_b128 v216, v[236:239]
	s_branch .Lp9m_pro_done
.Lp9m_pro_g1:
	s_waitcnt vmcnt(7)
.Lp9m_pro_done:
	s_add_i32 s50, s76, 4
	s_cmp_lt_i32 s50, 1
	s_waitcnt lgkmcnt(0)
	s_barrier
	s_cbranch_scc1 .LBB0_1369
	s_add_i32 s51, s77, s76
	s_add_u32 s46, s46, 0xc201000
	s_addc_u32 s47, s47, 0
	v_add_u32_e32 v22, v19, v20
	v_mov_b32_e32 v23, v145
	s_or_b32 s4, s4, s78
	v_lshl_add_u64 v[154:155], s[46:47], 0, v[22:23]
	s_add_u32 s46, s4, 0x23b20000
	v_mov_b32_e32 v17, v145
	s_addc_u32 s47, s5, 0
	v_lshl_add_u64 v[156:157], s[46:47], 0, v[16:17]
	v_lshlrev_b32_e32 v16, 9, v163
	v_and_b32_e32 v16, 0x18000, v16
	v_lshlrev_b32_e32 v17, 13, v18
	v_or3_b32 v16, v16, v17, v21
	v_mov_b32_e32 v17, v145
	v_mov_b32_e32 v30, v145
	v_mov_b32_e32 v31, v145
	v_lshl_add_u64 v[158:159], s[4:5], 0, v[16:17]
	v_mov_b32_e32 v16, v145
	v_mov_b32_e32 v18, v145
	v_mov_b32_e32 v19, v145
	v_mov_b32_e32 v20, v145
	v_mov_b32_e32 v21, v145
	v_mov_b32_e32 v22, v145
	v_mov_b32_e32 v24, v145
	v_mov_b32_e32 v25, v145
	v_mov_b32_e32 v26, v145
	v_mov_b32_e32 v27, v145
	v_mov_b32_e32 v28, v145
	v_mov_b32_e32 v29, v145
	v_mov_b64_e32 v[46:47], v[30:31]
	v_mul_u32_u24_e32 v173, 0x90, v162
	v_mul_u32_u24_e32 v171, 0x50, v162
	s_add_i32 s52, s76, 3
	s_mov_b32 s54, 0
	s_mov_b64 s[4:5], -1
	v_mov_b32_e32 v164, 0
	v_mov_b32_e32 v165, 0
	v_mov_b64_e32 v[44:45], v[28:29]
	v_mov_b64_e32 v[42:43], v[26:27]
	v_mov_b64_e32 v[40:41], v[24:25]
	v_mov_b64_e32 v[38:39], v[22:23]
	v_mov_b64_e32 v[36:37], v[20:21]
	v_mov_b64_e32 v[34:35], v[18:19]
	v_mov_b64_e32 v[32:33], v[16:17]
.LBB0_1335:
	s_add_i32 s53, s54, 1
	s_cmp_lt_i32 s53, s50
	s_cselect_b64 s[46:47], -1, 0
	s_add_i32 s89, s54, 2
	s_cmp_ge_i32 s89, s50
	s_cbranch_scc1 .LBB0_1341
	s_xor_b32 s89, s54, s88
	s_bitcmp1_b32 s89, 0
	s_cbranch_scc1 .LBB0_1341
	global_load_dwordx4 v[220:223], v211, s[82:83]
	global_load_dwordx4 v[224:227], v218, s[82:83]
	global_load_dwordx2 v[228:229], v212, s[84:85]
	global_load_dwordx2 v[230:231], v212, s[84:85] offset:2048
	global_load_dwordx2 v[232:233], v217, s[84:85]
	global_load_dwordx2 v[234:235], v217, s[84:85] offset:2048
	global_load_dwordx4 v[236:239], v213, s[86:87]
	s_add_u32 s82, s82, 0x40000
	s_addc_u32 s83, s83, 0
	s_add_u32 s84, s84, 0x40000
	s_addc_u32 s85, s85, 0
	s_add_u32 s86, s86, 0x2000
	s_addc_u32 s87, s87, 0

.LBB0_1350:
	s_andn2_b64 vcc, exec, s[46:47]
	s_cbranch_vccnz .LBB0_1356
	s_xor_b32 s89, s54, s88
	s_bitcmp0_b32 s89, 0
	s_cbranch_scc1 .LBB0_1356
	s_waitcnt vmcnt(0)
	ds_write_b128 v214, v[220:223]
	ds_write_b128 v214, v[224:227] offset:4608
	v_perm_b32 v240, v230, v228, s70
	v_perm_b32 v241, v234, v232, s70
	v_perm_b32 v242, v230, v228, s71
	v_perm_b32 v243, v234, v232, s71
	ds_write2_b64 v215, v[240:241], v[242:243] offset0:128 offset1:146
	v_perm_b32 v244, v231, v229, s70
	v_perm_b32 v245, v235, v233, s70
	v_perm_b32 v246, v231, v229, s71
	v_perm_b32 v247, v235, v233, s71
	ds_write2_b64 v215, v[244:245], v[246:247] offset0:164 offset1:182
	ds_write_b128 v216, v[236:239]
.LBB0_1356:
	s_cmp_eq_u32 s52, s53
	s_waitcnt lgkmcnt(0)
	s_barrier
	s_cbranch_scc1 .LBB0_1359
	s_mov_b32 s54, s53
	s_branch .LBB0_1335

.LBB0_1536:
	s_lshl_b32 s30, s58, 8
	s_add_i32 s30, s30, s48
	v_or_b32_e32 v154, s30, v158
	v_cmp_lt_i32_e32 vcc, s53, v154
	s_and_saveexec_b64 s[28:29], vcc
	s_xor_b64 s[28:29], exec, s[28:29]
	v_add_u32_e32 v150, 0xffff0000, v154
	v_mov_b32_e32 v151, v137
	v_lshlrev_b64 v[152:153], 12, v[150:151]
	v_lshrrev_b32_e32 v150, 5, v150
	v_lshl_add_u64 v[156:157], s[16:17], 0, v[152:153]
	v_add_u32_e32 v150, 32, v150
	v_mov_b32_e32 v155, v137
	s_or_saveexec_b64 s[28:29], s[28:29]
	s_ashr_i32 s31, s30, 11
	s_xor_b64 exec, exec, s[28:29]
	v_ashrrev_i32_e32 v155, 31, v154
	v_lshlrev_b64 v[150:151], 12, v[154:155]
	v_lshl_add_u64 v[156:157], s[4:5], 0, v[150:151]
	v_mov_b32_e32 v150, s31
	s_or_b64 exec, exec, s[28:29]
	v_lshl_or_b32 v152, s57, 8, v160
	v_lshlrev_b64 v[166:167], 11, v[154:155]
	v_ashrrev_i32_e32 v153, 31, v152
	v_lshl_add_u64 v[166:167], s[6:7], 0, v[166:167]
	v_lshl_add_u64 v[178:179], v[152:153], 1, v[166:167]
	v_mov_b64_e32 v[170:171], s[18:19]
	global_load_dwordx4 v[166:169], v[178:179], off
	v_mad_i64_i32 v[170:171], s[28:29], v150, s54, v[170:171]
	v_lshlrev_b64 v[150:151], 2, v[152:153]
	v_lshl_add_u64 v[180:181], v[170:171], 0, v[150:151]
	global_load_dwordx4 v[170:173], v[180:181], off
	global_load_dwordx4 v[174:177], v[180:181], off offset:16
	global_load_dwordx4 v[186:189], v[178:179], off offset:64
	global_load_dwordx4 v[190:193], v[180:181], off offset:128
	global_load_dwordx4 v[194:197], v[180:181], off offset:144
	v_lshl_add_u64 v[156:157], v[138:139], 2, v[156:157]
	v_lshl_add_u64 v[156:157], v[140:141], 2, v[156:157]
	v_lshl_add_u64 v[156:157], v[156:157], 0, v[136:137]
	v_lshl_add_u64 v[156:157], v[156:157], 0, v[150:151]
	s_waitcnt vmcnt(3)
	v_lshlrev_b32_e32 v182, 16, v166
	v_and_b32_e32 v183, 0xffff0000, v166
	v_lshlrev_b32_e32 v166, 16, v167
	v_and_b32_e32 v167, 0xffff0000, v167
	v_lshlrev_b32_e32 v184, 16, v168
	v_and_b32_e32 v185, 0xffff0000, v168
	v_lshlrev_b32_e32 v168, 16, v169
	v_and_b32_e32 v169, 0xffff0000, v169
	v_pk_fma_f32 v[122:123], v[122:123], v[172:173], v[166:167]
	v_pk_fma_f32 v[120:121], v[120:121], v[170:171], v[182:183]
	v_pk_fma_f32 v[126:127], v[126:127], v[176:177], v[168:169]
	v_pk_fma_f32 v[124:125], v[124:125], v[174:175], v[184:185]
	ds_write_b128 v164, v[120:123]
	ds_write_b128 v164, v[124:127] offset:16
	s_waitcnt lgkmcnt(0)
	ds_read_b128 v[120:123], v165
	ds_read_b128 v[124:127], v165 offset:1152
	v_add_co_u32_e32 v170, vcc, s49, v156
	s_nop 1
	v_addc_co_u32_e32 v171, vcc, 0, v157, vcc
	s_waitcnt lgkmcnt(0)
	global_store_dwordx4 v[156:157], v[120:123], off nt
	global_store_dwordx4 v[170:171], v[124:127], off nt
	s_waitcnt lgkmcnt(0)
	s_waitcnt vmcnt(4)
	v_lshlrev_b32_e32 v172, 16, v186
	v_and_b32_e32 v173, 0xffff0000, v186
	v_lshlrev_b32_e32 v120, 16, v187
	v_and_b32_e32 v121, 0xffff0000, v187
	v_lshlrev_b32_e32 v174, 16, v188
	v_and_b32_e32 v175, 0xffff0000, v188
	v_lshlrev_b32_e32 v122, 16, v189
	v_and_b32_e32 v123, 0xffff0000, v189
	s_waitcnt vmcnt(3)
	v_pk_fma_f32 v[118:119], v[118:119], v[192:193], v[120:121]
	v_pk_fma_f32 v[116:117], v[116:117], v[190:191], v[172:173]
	s_waitcnt vmcnt(2)
	v_pk_fma_f32 v[114:115], v[114:115], v[196:197], v[122:123]
	v_pk_fma_f32 v[112:113], v[112:113], v[194:195], v[174:175]
	ds_write_b128 v164, v[116:119]
	ds_write_b128 v164, v[112:115] offset:16
	s_waitcnt lgkmcnt(0)
	ds_read_b128 v[112:115], v165
	ds_read_b128 v[116:119], v165 offset:1152
	s_waitcnt lgkmcnt(1)
	global_store_dwordx4 v[156:157], v[112:115], off offset:128 nt
	s_waitcnt lgkmcnt(0)
	global_store_dwordx4 v[170:171], v[116:119], off offset:128 nt
	s_waitcnt lgkmcnt(0)
	v_or_b32_e32 v114, 16, v154
	v_cmp_lt_i32_e32 vcc, s53, v114
	s_and_saveexec_b64 s[28:29], vcc
	s_xor_b64 s[28:29], exec, s[28:29]
	v_add_u32_e32 v116, 0xffff0010, v154
	v_mov_b32_e32 v117, v137
	v_lshlrev_b64 v[112:113], 12, v[116:117]
	v_lshrrev_b32_e32 v115, 5, v116
	v_lshl_add_u64 v[112:113], s[16:17], 0, v[112:113]
	v_add_u32_e32 v116, 32, v115
	v_mov_b32_e32 v115, v137
	s_andn2_saveexec_b64 s[28:29], s[28:29]
	v_ashrrev_i32_e32 v115, 31, v114
	v_lshlrev_b64 v[112:113], 12, v[114:115]
	v_lshl_add_u64 v[112:113], s[4:5], 0, v[112:113]
	v_mov_b32_e32 v116, s31
	s_or_b64 exec, exec, s[28:29]
	v_lshlrev_b64 v[114:115], 11, v[114:115]
	v_lshl_add_u64 v[114:115], s[6:7], 0, v[114:115]
	v_lshl_add_u64 v[126:127], v[152:153], 1, v[114:115]
	v_mov_b64_e32 v[114:115], s[18:19]
	global_load_dwordx4 v[118:121], v[126:127], off
	v_mad_i64_i32 v[114:115], s[28:29], v116, s54, v[114:115]
	v_lshl_add_u64 v[156:157], v[114:115], 0, v[150:151]
	global_load_dwordx4 v[114:117], v[156:157], off
	global_load_dwordx4 v[122:125], v[156:157], off offset:16
	global_load_dwordx4 v[186:189], v[126:127], off offset:64
	global_load_dwordx4 v[190:193], v[156:157], off offset:128
	global_load_dwordx4 v[194:197], v[156:157], off offset:144
	v_lshl_add_u64 v[112:113], v[138:139], 2, v[112:113]
	v_lshl_add_u64 v[112:113], v[140:141], 2, v[112:113]
	v_lshl_add_u64 v[112:113], v[112:113], 0, v[136:137]
	v_lshl_add_u64 v[166:167], v[112:113], 0, v[150:151]
	s_waitcnt vmcnt(5)
	v_lshlrev_b32_e32 v112, 16, v118
	v_and_b32_e32 v113, 0xffff0000, v118
	v_lshlrev_b32_e32 v118, 16, v119
	v_and_b32_e32 v119, 0xffff0000, v119
	v_lshlrev_b32_e32 v168, 16, v120
	v_and_b32_e32 v169, 0xffff0000, v120
	v_lshlrev_b32_e32 v120, 16, v121
	v_and_b32_e32 v121, 0xffff0000, v121
	s_waitcnt vmcnt(4)
	v_pk_fma_f32 v[110:111], v[110:111], v[116:117], v[118:119]
	v_pk_fma_f32 v[108:109], v[108:109], v[114:115], v[112:113]
	s_waitcnt vmcnt(3)
	v_pk_fma_f32 v[106:107], v[106:107], v[124:125], v[120:121]
	v_pk_fma_f32 v[104:105], v[104:105], v[122:123], v[168:169]
	ds_write_b128 v164, v[108:111]
	ds_write_b128 v164, v[104:107] offset:16
	s_waitcnt lgkmcnt(0)
	ds_read_b128 v[104:107], v165
	ds_read_b128 v[108:111], v165 offset:1152
	v_add_co_u32_e32 v116, vcc, s49, v166
	s_nop 1
	v_addc_co_u32_e32 v117, vcc, 0, v167, vcc
	s_waitcnt lgkmcnt(1)
	global_store_dwordx4 v[166:167], v[104:107], off nt
	s_waitcnt lgkmcnt(0)
	global_store_dwordx4 v[116:117], v[108:111], off nt
	s_waitcnt lgkmcnt(0)
	s_waitcnt vmcnt(4)
	v_lshlrev_b32_e32 v118, 16, v186
	v_and_b32_e32 v119, 0xffff0000, v186
	v_lshlrev_b32_e32 v104, 16, v187
	v_and_b32_e32 v105, 0xffff0000, v187
	v_lshlrev_b32_e32 v120, 16, v188
	v_and_b32_e32 v121, 0xffff0000, v188
	v_lshlrev_b32_e32 v106, 16, v189
	v_and_b32_e32 v107, 0xffff0000, v189
	s_waitcnt vmcnt(3)
	v_pk_fma_f32 v[102:103], v[102:103], v[192:193], v[104:105]
	v_pk_fma_f32 v[100:101], v[100:101], v[190:191], v[118:119]
	s_waitcnt vmcnt(2)
	v_pk_fma_f32 v[98:99], v[98:99], v[196:197], v[106:107]
	v_pk_fma_f32 v[96:97], v[96:97], v[194:195], v[120:121]
	ds_write_b128 v164, v[100:103]
	ds_write_b128 v164, v[96:99] offset:16
	s_waitcnt lgkmcnt(0)
	ds_read_b128 v[96:99], v165
	ds_read_b128 v[100:103], v165 offset:1152
	s_waitcnt lgkmcnt(1)
	global_store_dwordx4 v[166:167], v[96:99], off offset:128 nt
	s_waitcnt lgkmcnt(0)
	global_store_dwordx4 v[116:117], v[100:103], off offset:128 nt
	s_waitcnt lgkmcnt(0)
	v_or_b32_e32 v98, 32, v154
	v_cmp_lt_i32_e32 vcc, s53, v98
	s_and_saveexec_b64 s[28:29], vcc
	s_xor_b64 s[28:29], exec, s[28:29]
	v_add_u32_e32 v100, 0xffff0020, v154
	v_mov_b32_e32 v101, v137
	v_lshlrev_b64 v[96:97], 12, v[100:101]
	v_lshrrev_b32_e32 v99, 5, v100
	v_lshl_add_u64 v[96:97], s[16:17], 0, v[96:97]
	v_add_u32_e32 v100, 32, v99
	v_mov_b32_e32 v99, v137
	s_andn2_saveexec_b64 s[28:29], s[28:29]
	v_ashrrev_i32_e32 v99, 31, v98
	v_lshlrev_b64 v[96:97], 12, v[98:99]
	v_lshl_add_u64 v[96:97], s[4:5], 0, v[96:97]
	v_mov_b32_e32 v100, s31
	s_or_b64 exec, exec, s[28:29]
	v_lshlrev_b64 v[98:99], 11, v[98:99]
	v_lshl_add_u64 v[98:99], s[6:7], 0, v[98:99]
	v_lshl_add_u64 v[110:111], v[152:153], 1, v[98:99]
	v_mov_b64_e32 v[98:99], s[18:19]
	global_load_dwordx4 v[102:105], v[110:111], off
	v_mad_i64_i32 v[98:99], s[28:29], v100, s54, v[98:99]
	v_lshl_add_u64 v[112:113], v[98:99], 0, v[150:151]
	global_load_dwordx4 v[98:101], v[112:113], off
	global_load_dwordx4 v[106:109], v[112:113], off offset:16
	global_load_dwordx4 v[186:189], v[110:111], off offset:64
	global_load_dwordx4 v[190:193], v[112:113], off offset:128
	global_load_dwordx4 v[194:197], v[112:113], off offset:144
	v_lshl_add_u64 v[96:97], v[138:139], 2, v[96:97]
	v_lshl_add_u64 v[96:97], v[140:141], 2, v[96:97]
	v_lshl_add_u64 v[96:97], v[96:97], 0, v[136:137]
	v_lshl_add_u64 v[114:115], v[96:97], 0, v[150:151]
	s_waitcnt vmcnt(5)
	v_lshlrev_b32_e32 v96, 16, v102
	v_and_b32_e32 v97, 0xffff0000, v102
	v_lshlrev_b32_e32 v102, 16, v103
	v_and_b32_e32 v103, 0xffff0000, v103
	v_lshlrev_b32_e32 v116, 16, v104
	v_and_b32_e32 v117, 0xffff0000, v104
	v_lshlrev_b32_e32 v104, 16, v105
	v_and_b32_e32 v105, 0xffff0000, v105
	s_waitcnt vmcnt(4)
	v_pk_fma_f32 v[94:95], v[94:95], v[100:101], v[102:103]
	v_pk_fma_f32 v[92:93], v[92:93], v[98:99], v[96:97]
	s_waitcnt vmcnt(3)
	v_pk_fma_f32 v[90:91], v[90:91], v[108:109], v[104:105]
	v_pk_fma_f32 v[88:89], v[88:89], v[106:107], v[116:117]
	ds_write_b128 v164, v[92:95]
	ds_write_b128 v164, v[88:91] offset:16
	s_waitcnt lgkmcnt(0)
	ds_read_b128 v[88:91], v165
	ds_read_b128 v[92:95], v165 offset:1152
	v_add_co_u32_e32 v100, vcc, s49, v114
	s_nop 1
	v_addc_co_u32_e32 v101, vcc, 0, v115, vcc
	s_waitcnt lgkmcnt(1)
	global_store_dwordx4 v[114:115], v[88:91], off nt
	s_waitcnt lgkmcnt(0)
	global_store_dwordx4 v[100:101], v[92:95], off nt
	s_waitcnt lgkmcnt(0)
	s_waitcnt vmcnt(4)
	v_lshlrev_b32_e32 v102, 16, v186
	v_and_b32_e32 v103, 0xffff0000, v186
	v_lshlrev_b32_e32 v88, 16, v187
	v_and_b32_e32 v89, 0xffff0000, v187
	v_lshlrev_b32_e32 v104, 16, v188
	v_and_b32_e32 v105, 0xffff0000, v188
	v_lshlrev_b32_e32 v90, 16, v189
	v_and_b32_e32 v91, 0xffff0000, v189
	s_waitcnt vmcnt(3)
	v_pk_fma_f32 v[86:87], v[86:87], v[192:193], v[88:89]
	v_pk_fma_f32 v[84:85], v[84:85], v[190:191], v[102:103]
	s_waitcnt vmcnt(2)
	v_pk_fma_f32 v[82:83], v[82:83], v[196:197], v[90:91]
	v_pk_fma_f32 v[80:81], v[80:81], v[194:195], v[104:105]
	ds_write_b128 v164, v[84:87]
	ds_write_b128 v164, v[80:83] offset:16
	s_waitcnt lgkmcnt(0)
	ds_read_b128 v[80:83], v165
	ds_read_b128 v[84:87], v165 offset:1152
	s_waitcnt lgkmcnt(1)
	global_store_dwordx4 v[114:115], v[80:83], off offset:128 nt
	s_waitcnt lgkmcnt(0)
	global_store_dwordx4 v[100:101], v[84:87], off offset:128 nt
	s_waitcnt lgkmcnt(0)
	v_or_b32_e32 v82, 48, v154
	v_cmp_lt_i32_e32 vcc, s53, v82
	s_and_saveexec_b64 s[28:29], vcc
	s_xor_b64 s[28:29], exec, s[28:29]
	v_add_u32_e32 v84, 0xffff0030, v154
	v_mov_b32_e32 v85, v137
	v_lshlrev_b64 v[80:81], 12, v[84:85]
	v_lshrrev_b32_e32 v83, 5, v84
	v_lshl_add_u64 v[80:81], s[16:17], 0, v[80:81]
	v_add_u32_e32 v84, 32, v83
	v_mov_b32_e32 v83, v137
	s_andn2_saveexec_b64 s[28:29], s[28:29]
	v_ashrrev_i32_e32 v83, 31, v82
	v_lshlrev_b64 v[80:81], 12, v[82:83]
	v_lshl_add_u64 v[80:81], s[4:5], 0, v[80:81]
	v_mov_b32_e32 v84, s31
	s_or_b64 exec, exec, s[28:29]
	v_lshlrev_b64 v[82:83], 11, v[82:83]
	v_lshl_add_u64 v[82:83], s[6:7], 0, v[82:83]
	v_lshl_add_u64 v[94:95], v[152:153], 1, v[82:83]
	v_mov_b64_e32 v[82:83], s[18:19]
	global_load_dwordx4 v[86:89], v[94:95], off
	v_mad_i64_i32 v[82:83], s[28:29], v84, s54, v[82:83]
	v_lshl_add_u64 v[96:97], v[82:83], 0, v[150:151]
	global_load_dwordx4 v[82:85], v[96:97], off
	global_load_dwordx4 v[90:93], v[96:97], off offset:16
	global_load_dwordx4 v[186:189], v[94:95], off offset:64
	global_load_dwordx4 v[190:193], v[96:97], off offset:128
	global_load_dwordx4 v[194:197], v[96:97], off offset:144
	v_lshl_add_u64 v[80:81], v[138:139], 2, v[80:81]
	v_lshl_add_u64 v[80:81], v[140:141], 2, v[80:81]
	v_lshl_add_u64 v[80:81], v[80:81], 0, v[136:137]
	v_lshl_add_u64 v[98:99], v[80:81], 0, v[150:151]
	s_addk_i32 s30, 0x80
	s_waitcnt vmcnt(5)
	v_lshlrev_b32_e32 v80, 16, v86
	v_and_b32_e32 v81, 0xffff0000, v86
	v_lshlrev_b32_e32 v86, 16, v87
	v_and_b32_e32 v87, 0xffff0000, v87
	v_lshlrev_b32_e32 v100, 16, v88
	v_and_b32_e32 v101, 0xffff0000, v88
	v_lshlrev_b32_e32 v88, 16, v89
	v_and_b32_e32 v89, 0xffff0000, v89
	s_waitcnt vmcnt(4)
	v_pk_fma_f32 v[78:79], v[78:79], v[84:85], v[86:87]
	v_pk_fma_f32 v[76:77], v[76:77], v[82:83], v[80:81]
	s_waitcnt vmcnt(3)
	v_pk_fma_f32 v[74:75], v[74:75], v[92:93], v[88:89]
	v_pk_fma_f32 v[72:73], v[72:73], v[90:91], v[100:101]
	ds_write_b128 v164, v[76:79]
	ds_write_b128 v164, v[72:75] offset:16
	s_waitcnt lgkmcnt(0)
	ds_read_b128 v[72:75], v165
	ds_read_b128 v[76:79], v165 offset:1152
	v_add_co_u32_e32 v84, vcc, s49, v98
	s_nop 1
	v_addc_co_u32_e32 v85, vcc, 0, v99, vcc
	s_waitcnt lgkmcnt(1)
	global_store_dwordx4 v[98:99], v[72:75], off nt
	s_waitcnt lgkmcnt(0)
	global_store_dwordx4 v[84:85], v[76:79], off nt
	s_waitcnt lgkmcnt(0)
	s_waitcnt vmcnt(4)
	v_lshlrev_b32_e32 v86, 16, v186
	v_and_b32_e32 v87, 0xffff0000, v186
	v_lshlrev_b32_e32 v72, 16, v187
	v_and_b32_e32 v73, 0xffff0000, v187
	v_lshlrev_b32_e32 v88, 16, v188
	v_and_b32_e32 v89, 0xffff0000, v188
	v_lshlrev_b32_e32 v74, 16, v189
	v_and_b32_e32 v75, 0xffff0000, v189
	s_waitcnt vmcnt(3)
	v_pk_fma_f32 v[70:71], v[70:71], v[192:193], v[72:73]
	v_pk_fma_f32 v[68:69], v[68:69], v[190:191], v[86:87]
	s_waitcnt vmcnt(2)
	v_pk_fma_f32 v[66:67], v[66:67], v[196:197], v[74:75]
	v_pk_fma_f32 v[64:65], v[64:65], v[194:195], v[88:89]
	ds_write_b128 v164, v[68:71]
	ds_write_b128 v164, v[64:67] offset:16
	s_waitcnt lgkmcnt(0)
	ds_read_b128 v[64:67], v165
	ds_read_b128 v[68:71], v165 offset:1152
	s_waitcnt lgkmcnt(1)
	global_store_dwordx4 v[98:99], v[64:67], off offset:128 nt
	s_waitcnt lgkmcnt(0)
	global_store_dwordx4 v[84:85], v[68:71], off offset:128 nt
	s_waitcnt lgkmcnt(0)
	v_or_b32_e32 v64, s30, v158
	v_cmp_lt_i32_e32 vcc, s53, v64
	s_and_saveexec_b64 s[28:29], vcc
	s_xor_b64 s[28:29], exec, s[28:29]
	v_add_u32_e32 v68, 0xffff0000, v64
	v_mov_b32_e32 v69, v137
	v_lshlrev_b64 v[66:67], 12, v[68:69]
	v_lshrrev_b32_e32 v65, 5, v68
	v_lshl_add_u64 v[66:67], s[16:17], 0, v[66:67]
	v_add_u32_e32 v68, 32, v65
	v_mov_b32_e32 v65, v137
	s_or_saveexec_b64 s[28:29], s[28:29]
	s_ashr_i32 s30, s30, 11
	s_xor_b64 exec, exec, s[28:29]
	v_ashrrev_i32_e32 v65, 31, v64
	v_lshlrev_b64 v[66:67], 12, v[64:65]
	v_lshl_add_u64 v[66:67], s[4:5], 0, v[66:67]
	v_mov_b32_e32 v68, s30
	s_or_b64 exec, exec, s[28:29]
	v_lshlrev_b64 v[70:71], 11, v[64:65]
	v_lshl_add_u64 v[70:71], s[6:7], 0, v[70:71]
	v_lshl_add_u64 v[82:83], v[152:153], 1, v[70:71]
	v_mov_b64_e32 v[74:75], s[18:19]
	global_load_dwordx4 v[70:73], v[82:83], off
	v_mad_i64_i32 v[68:69], s[28:29], v68, s54, v[74:75]
	v_lshl_add_u64 v[68:69], v[68:69], 0, v[150:151]
	global_load_dwordx4 v[74:77], v[68:69], off
	global_load_dwordx4 v[78:81], v[68:69], off offset:16
	global_load_dwordx4 v[186:189], v[82:83], off offset:64
	global_load_dwordx4 v[190:193], v[68:69], off offset:128
	global_load_dwordx4 v[194:197], v[68:69], off offset:144
	v_lshl_add_u64 v[66:67], v[138:139], 2, v[66:67]
	v_lshl_add_u64 v[66:67], v[140:141], 2, v[66:67]
	v_lshl_add_u64 v[66:67], v[66:67], 0, v[136:137]
	v_lshl_add_u64 v[84:85], v[66:67], 0, v[150:151]
	s_waitcnt vmcnt(5)
	v_lshlrev_b32_e32 v66, 16, v70
	v_and_b32_e32 v67, 0xffff0000, v70
	v_lshlrev_b32_e32 v70, 16, v71
	v_and_b32_e32 v71, 0xffff0000, v71
	v_lshlrev_b32_e32 v86, 16, v72
	v_and_b32_e32 v87, 0xffff0000, v72
	v_lshlrev_b32_e32 v72, 16, v73
	v_and_b32_e32 v73, 0xffff0000, v73
	s_waitcnt vmcnt(4)
	v_pk_fma_f32 v[62:63], v[62:63], v[76:77], v[70:71]
	v_pk_fma_f32 v[60:61], v[60:61], v[74:75], v[66:67]
	s_waitcnt vmcnt(3)
	v_pk_fma_f32 v[58:59], v[58:59], v[80:81], v[72:73]
	v_pk_fma_f32 v[56:57], v[56:57], v[78:79], v[86:87]
	ds_write_b128 v164, v[60:63]
	ds_write_b128 v164, v[56:59] offset:16
	s_waitcnt lgkmcnt(0)
	ds_read_b128 v[56:59], v165
	ds_read_b128 v[60:63], v165 offset:1152
	v_add_co_u32_e32 v70, vcc, s49, v84
	s_nop 1
	v_addc_co_u32_e32 v71, vcc, 0, v85, vcc
	s_waitcnt lgkmcnt(1)
	global_store_dwordx4 v[84:85], v[56:59], off nt
	s_waitcnt lgkmcnt(0)
	global_store_dwordx4 v[70:71], v[60:63], off nt
	s_waitcnt lgkmcnt(0)
	s_nop 0
	s_waitcnt vmcnt(4)
	v_lshlrev_b32_e32 v72, 16, v186
	v_and_b32_e32 v73, 0xffff0000, v186
	v_lshlrev_b32_e32 v56, 16, v187
	v_and_b32_e32 v57, 0xffff0000, v187
	v_lshlrev_b32_e32 v74, 16, v188
	v_and_b32_e32 v75, 0xffff0000, v188
	v_lshlrev_b32_e32 v58, 16, v189
	v_and_b32_e32 v59, 0xffff0000, v189
	s_waitcnt vmcnt(3)
	v_pk_fma_f32 v[54:55], v[54:55], v[192:193], v[56:57]
	v_pk_fma_f32 v[52:53], v[52:53], v[190:191], v[72:73]
	s_waitcnt vmcnt(2)
	v_pk_fma_f32 v[50:51], v[50:51], v[196:197], v[58:59]
	v_pk_fma_f32 v[48:49], v[48:49], v[194:195], v[74:75]
	ds_write_b128 v164, v[52:55]
	ds_write_b128 v164, v[48:51] offset:16
	s_waitcnt lgkmcnt(0)
	ds_read_b128 v[48:51], v165
	ds_read_b128 v[52:55], v165 offset:1152
	s_waitcnt lgkmcnt(1)
	global_store_dwordx4 v[84:85], v[48:51], off offset:128 nt
	s_waitcnt lgkmcnt(0)
	global_store_dwordx4 v[70:71], v[52:55], off offset:128 nt
	s_waitcnt lgkmcnt(0)
	v_or_b32_e32 v50, 16, v64
	v_cmp_lt_i32_e32 vcc, s53, v50
	s_and_saveexec_b64 s[28:29], vcc
	s_xor_b64 s[28:29], exec, s[28:29]
	v_add_u32_e32 v52, 0xffff0010, v64
	v_mov_b32_e32 v53, v137
	v_lshlrev_b64 v[48:49], 12, v[52:53]
	v_lshrrev_b32_e32 v51, 5, v52
	v_lshl_add_u64 v[48:49], s[16:17], 0, v[48:49]
	v_add_u32_e32 v52, 32, v51
	v_mov_b32_e32 v51, v137
	s_andn2_saveexec_b64 s[28:29], s[28:29]
	v_ashrrev_i32_e32 v51, 31, v50
	v_lshlrev_b64 v[48:49], 12, v[50:51]
	v_lshl_add_u64 v[48:49], s[4:5], 0, v[48:49]
	v_mov_b32_e32 v52, s30
	s_or_b64 exec, exec, s[28:29]
	v_lshlrev_b64 v[50:51], 11, v[50:51]
	v_lshl_add_u64 v[50:51], s[6:7], 0, v[50:51]
	v_lshl_add_u64 v[62:63], v[152:153], 1, v[50:51]
	v_mov_b64_e32 v[50:51], s[18:19]
	global_load_dwordx4 v[54:57], v[62:63], off
	v_mad_i64_i32 v[50:51], s[28:29], v52, s54, v[50:51]
	v_lshl_add_u64 v[66:67], v[50:51], 0, v[150:151]
	global_load_dwordx4 v[50:53], v[66:67], off
	global_load_dwordx4 v[58:61], v[66:67], off offset:16
	global_load_dwordx4 v[186:189], v[62:63], off offset:64
	global_load_dwordx4 v[190:193], v[66:67], off offset:128
	global_load_dwordx4 v[194:197], v[66:67], off offset:144
	v_lshl_add_u64 v[48:49], v[138:139], 2, v[48:49]
	v_lshl_add_u64 v[48:49], v[140:141], 2, v[48:49]
	v_lshl_add_u64 v[48:49], v[48:49], 0, v[136:137]
	v_lshl_add_u64 v[68:69], v[48:49], 0, v[150:151]
	s_waitcnt vmcnt(5)
	v_lshlrev_b32_e32 v48, 16, v54
	v_and_b32_e32 v49, 0xffff0000, v54
	v_lshlrev_b32_e32 v54, 16, v55
	v_and_b32_e32 v55, 0xffff0000, v55
	v_lshlrev_b32_e32 v70, 16, v56
	v_and_b32_e32 v71, 0xffff0000, v56
	v_lshlrev_b32_e32 v56, 16, v57
	v_and_b32_e32 v57, 0xffff0000, v57
	s_waitcnt vmcnt(4)
	v_pk_fma_f32 v[46:47], v[46:47], v[52:53], v[54:55]
	v_pk_fma_f32 v[44:45], v[44:45], v[50:51], v[48:49]
	s_waitcnt vmcnt(3)
	v_pk_fma_f32 v[42:43], v[42:43], v[60:61], v[56:57]
	v_pk_fma_f32 v[40:41], v[40:41], v[58:59], v[70:71]
	ds_write_b128 v164, v[44:47]
	ds_write_b128 v164, v[40:43] offset:16
	s_waitcnt lgkmcnt(0)
	ds_read_b128 v[40:43], v165
	ds_read_b128 v[44:47], v165 offset:1152
	v_add_co_u32_e32 v52, vcc, s49, v68
	s_nop 1
	v_addc_co_u32_e32 v53, vcc, 0, v69, vcc
	s_waitcnt lgkmcnt(1)
	global_store_dwordx4 v[68:69], v[40:43], off nt
	s_waitcnt lgkmcnt(0)
	global_store_dwordx4 v[52:53], v[44:47], off nt
	s_waitcnt lgkmcnt(0)
	s_waitcnt vmcnt(4)
	v_lshlrev_b32_e32 v54, 16, v186
	v_and_b32_e32 v55, 0xffff0000, v186
	v_lshlrev_b32_e32 v40, 16, v187
	v_and_b32_e32 v41, 0xffff0000, v187
	v_lshlrev_b32_e32 v56, 16, v188
	v_and_b32_e32 v57, 0xffff0000, v188
	v_lshlrev_b32_e32 v42, 16, v189
	v_and_b32_e32 v43, 0xffff0000, v189
	s_waitcnt vmcnt(3)
	v_pk_fma_f32 v[38:39], v[38:39], v[192:193], v[40:41]
	v_pk_fma_f32 v[36:37], v[36:37], v[190:191], v[54:55]
	s_waitcnt vmcnt(2)
	v_pk_fma_f32 v[34:35], v[34:35], v[196:197], v[42:43]
	v_pk_fma_f32 v[32:33], v[32:33], v[194:195], v[56:57]
	ds_write_b128 v164, v[36:39]
	ds_write_b128 v164, v[32:35] offset:16
	s_waitcnt lgkmcnt(0)
	ds_read_b128 v[32:35], v165
	ds_read_b128 v[36:39], v165 offset:1152
	s_waitcnt lgkmcnt(1)
	global_store_dwordx4 v[68:69], v[32:35], off offset:128 nt
	s_waitcnt lgkmcnt(0)
	global_store_dwordx4 v[52:53], v[36:39], off offset:128 nt
	s_waitcnt lgkmcnt(0)
	v_or_b32_e32 v34, 32, v64
	v_cmp_lt_i32_e32 vcc, s53, v34
	s_and_saveexec_b64 s[28:29], vcc
	s_xor_b64 s[28:29], exec, s[28:29]
	v_add_u32_e32 v36, 0xffff0020, v64
	v_mov_b32_e32 v37, v137
	v_lshlrev_b64 v[32:33], 12, v[36:37]
	v_lshrrev_b32_e32 v35, 5, v36
	v_lshl_add_u64 v[32:33], s[16:17], 0, v[32:33]
	v_add_u32_e32 v36, 32, v35
	v_mov_b32_e32 v35, v137
	s_andn2_saveexec_b64 s[28:29], s[28:29]
	v_ashrrev_i32_e32 v35, 31, v34
	v_lshlrev_b64 v[32:33], 12, v[34:35]
	v_lshl_add_u64 v[32:33], s[4:5], 0, v[32:33]
	v_mov_b32_e32 v36, s30
	s_or_b64 exec, exec, s[28:29]
	v_lshlrev_b64 v[34:35], 11, v[34:35]
	v_lshl_add_u64 v[34:35], s[6:7], 0, v[34:35]
	v_lshl_add_u64 v[46:47], v[152:153], 1, v[34:35]
	v_mov_b64_e32 v[34:35], s[18:19]
	global_load_dwordx4 v[38:41], v[46:47], off
	v_mad_i64_i32 v[34:35], s[28:29], v36, s54, v[34:35]
	v_lshl_add_u64 v[48:49], v[34:35], 0, v[150:151]
	global_load_dwordx4 v[34:37], v[48:49], off
	global_load_dwordx4 v[42:45], v[48:49], off offset:16
	global_load_dwordx4 v[186:189], v[46:47], off offset:64
	global_load_dwordx4 v[190:193], v[48:49], off offset:128
	global_load_dwordx4 v[194:197], v[48:49], off offset:144
	v_lshl_add_u64 v[32:33], v[138:139], 2, v[32:33]
	v_lshl_add_u64 v[32:33], v[140:141], 2, v[32:33]
	v_lshl_add_u64 v[32:33], v[32:33], 0, v[136:137]
	v_lshl_add_u64 v[50:51], v[32:33], 0, v[150:151]
	s_waitcnt vmcnt(5)
	v_lshlrev_b32_e32 v32, 16, v38
	v_and_b32_e32 v33, 0xffff0000, v38
	v_lshlrev_b32_e32 v38, 16, v39
	v_and_b32_e32 v39, 0xffff0000, v39
	v_lshlrev_b32_e32 v52, 16, v40
	v_and_b32_e32 v53, 0xffff0000, v40
	v_lshlrev_b32_e32 v40, 16, v41
	v_and_b32_e32 v41, 0xffff0000, v41
	s_waitcnt vmcnt(4)
	v_pk_fma_f32 v[30:31], v[30:31], v[36:37], v[38:39]
	v_pk_fma_f32 v[28:29], v[28:29], v[34:35], v[32:33]
	s_waitcnt vmcnt(3)
	v_pk_fma_f32 v[26:27], v[26:27], v[44:45], v[40:41]
	v_pk_fma_f32 v[24:25], v[24:25], v[42:43], v[52:53]
	ds_write_b128 v164, v[28:31]
	ds_write_b128 v164, v[24:27] offset:16
	s_waitcnt lgkmcnt(0)
	ds_read_b128 v[24:27], v165
	ds_read_b128 v[28:31], v165 offset:1152
	v_add_co_u32_e32 v36, vcc, s49, v50
	s_nop 1
	v_addc_co_u32_e32 v37, vcc, 0, v51, vcc
	s_waitcnt lgkmcnt(1)
	global_store_dwordx4 v[50:51], v[24:27], off nt
	s_waitcnt lgkmcnt(0)
	global_store_dwordx4 v[36:37], v[28:31], off nt
	s_waitcnt lgkmcnt(0)
	s_waitcnt vmcnt(4)
	v_lshlrev_b32_e32 v38, 16, v186
	v_and_b32_e32 v39, 0xffff0000, v186
	v_lshlrev_b32_e32 v24, 16, v187
	v_and_b32_e32 v25, 0xffff0000, v187
	v_lshlrev_b32_e32 v40, 16, v188
	v_and_b32_e32 v41, 0xffff0000, v188
	v_lshlrev_b32_e32 v26, 16, v189
	v_and_b32_e32 v27, 0xffff0000, v189
	s_waitcnt vmcnt(3)
	v_pk_fma_f32 v[22:23], v[22:23], v[192:193], v[24:25]
	v_pk_fma_f32 v[20:21], v[20:21], v[190:191], v[38:39]
	s_waitcnt vmcnt(2)
	v_pk_fma_f32 v[18:19], v[18:19], v[196:197], v[26:27]
	v_pk_fma_f32 v[16:17], v[16:17], v[194:195], v[40:41]
	ds_write_b128 v164, v[20:23]
	ds_write_b128 v164, v[16:19] offset:16
	s_waitcnt lgkmcnt(0)
	ds_read_b128 v[16:19], v165
	ds_read_b128 v[20:23], v165 offset:1152
	s_waitcnt lgkmcnt(1)
	global_store_dwordx4 v[50:51], v[16:19], off offset:128 nt
	s_waitcnt lgkmcnt(0)
	global_store_dwordx4 v[36:37], v[20:23], off offset:128 nt
	s_waitcnt lgkmcnt(0)
	v_or_b32_e32 v18, 48, v64
	v_cmp_lt_i32_e32 vcc, s53, v18
	s_and_saveexec_b64 s[28:29], vcc
	s_xor_b64 s[28:29], exec, s[28:29]
	v_add_u32_e32 v20, 0xffff0030, v64
	v_mov_b32_e32 v21, v137
	v_lshlrev_b64 v[16:17], 12, v[20:21]
	v_lshrrev_b32_e32 v19, 5, v20
	v_lshl_add_u64 v[16:17], s[16:17], 0, v[16:17]
	v_add_u32_e32 v20, 32, v19
	v_mov_b32_e32 v19, v137
	s_andn2_saveexec_b64 s[28:29], s[28:29]
	v_ashrrev_i32_e32 v19, 31, v18
	v_lshlrev_b64 v[16:17], 12, v[18:19]
	v_lshl_add_u64 v[16:17], s[4:5], 0, v[16:17]
	v_mov_b32_e32 v20, s30
	s_or_b64 exec, exec, s[28:29]
	v_lshlrev_b64 v[18:19], 11, v[18:19]
	v_lshl_add_u64 v[18:19], s[6:7], 0, v[18:19]
	v_lshl_add_u64 v[30:31], v[152:153], 1, v[18:19]
	v_mov_b64_e32 v[18:19], s[18:19]
	global_load_dwordx4 v[22:25], v[30:31], off
	v_mad_i64_i32 v[18:19], s[28:29], v20, s54, v[18:19]
	v_lshl_add_u64 v[32:33], v[18:19], 0, v[150:151]
	global_load_dwordx4 v[18:21], v[32:33], off
	global_load_dwordx4 v[26:29], v[32:33], off offset:16
	global_load_dwordx4 v[186:189], v[30:31], off offset:64
	global_load_dwordx4 v[190:193], v[32:33], off offset:128
	global_load_dwordx4 v[194:197], v[32:33], off offset:144
	v_lshl_add_u64 v[16:17], v[138:139], 2, v[16:17]
	v_lshl_add_u64 v[16:17], v[140:141], 2, v[16:17]
	v_lshl_add_u64 v[16:17], v[16:17], 0, v[136:137]
	v_lshl_add_u64 v[34:35], v[16:17], 0, v[150:151]
	s_waitcnt vmcnt(5)
	v_lshlrev_b32_e32 v16, 16, v22
	v_and_b32_e32 v17, 0xffff0000, v22
	v_lshlrev_b32_e32 v22, 16, v23
	v_and_b32_e32 v23, 0xffff0000, v23
	v_lshlrev_b32_e32 v36, 16, v24
	v_and_b32_e32 v37, 0xffff0000, v24
	v_lshlrev_b32_e32 v24, 16, v25
	v_and_b32_e32 v25, 0xffff0000, v25
	s_waitcnt vmcnt(4)
	v_pk_fma_f32 v[14:15], v[14:15], v[20:21], v[22:23]
	v_pk_fma_f32 v[12:13], v[12:13], v[18:19], v[16:17]
	s_waitcnt vmcnt(3)
	v_pk_fma_f32 v[10:11], v[10:11], v[28:29], v[24:25]
	v_pk_fma_f32 v[8:9], v[8:9], v[26:27], v[36:37]
	ds_write_b128 v164, v[12:15]
	ds_write_b128 v164, v[8:11] offset:16
	s_waitcnt lgkmcnt(0)
	ds_read_b128 v[8:11], v165
	ds_read_b128 v[12:15], v165 offset:1152
	v_add_co_u32_e32 v20, vcc, s49, v34
	s_nop 1
	v_addc_co_u32_e32 v21, vcc, 0, v35, vcc
	s_waitcnt lgkmcnt(1)
	global_store_dwordx4 v[34:35], v[8:11], off nt
	s_waitcnt lgkmcnt(0)
	global_store_dwordx4 v[20:21], v[12:15], off nt
	s_waitcnt lgkmcnt(0)
	s_and_b64 vcc, exec, s[0:1]
	s_mov_b64 s[0:1], -1
	s_waitcnt vmcnt(4)
	v_lshlrev_b32_e32 v22, 16, v186
	v_and_b32_e32 v23, 0xffff0000, v186
	v_lshlrev_b32_e32 v8, 16, v187
	v_and_b32_e32 v9, 0xffff0000, v187
	v_lshlrev_b32_e32 v24, 16, v188
	v_and_b32_e32 v25, 0xffff0000, v188
	v_lshlrev_b32_e32 v10, 16, v189
	v_and_b32_e32 v11, 0xffff0000, v189
	s_waitcnt vmcnt(3)
	v_pk_fma_f32 v[6:7], v[6:7], v[192:193], v[8:9]
	v_pk_fma_f32 v[4:5], v[4:5], v[190:191], v[22:23]
	s_waitcnt vmcnt(2)
	v_pk_fma_f32 v[2:3], v[2:3], v[196:197], v[10:11]
	v_pk_fma_f32 v[0:1], v[0:1], v[194:195], v[24:25]
	ds_write_b128 v164, v[4:7]
	ds_write_b128 v164, v[0:3] offset:16
	s_waitcnt lgkmcnt(0)
	ds_read_b128 v[0:3], v165
	ds_read_b128 v[4:7], v165 offset:1152
	s_waitcnt lgkmcnt(1)
	global_store_dwordx4 v[34:35], v[0:3], off offset:128 nt
	s_waitcnt lgkmcnt(0)
	global_store_dwordx4 v[20:21], v[4:7], off offset:128 nt
	s_waitcnt lgkmcnt(0)
	s_cbranch_vccnz .LBB0_1520
	s_andn2_b64 vcc, exec, s[14:15]
	s_cbranch_vccnz .LBB0_1519
	s_barrier
	s_branch .LBB0_1519
